# combo9 + every 8-byte instruction inside the 7 GEMM K-loops placed on an 8-byte boundary (s_nop fillers), loop regions grown by multiples of 64 B
# baseline (speedup 1.0000x reference)
.LBB0_324:
	s_add_i32 vcc_lo, s66, 2
	s_add_u32 s34, s8, 0xfff00080
	s_addc_u32 s35, s9, -1
	s_nop 0
	s_add_i32 s89, 0, 0x10000
	s_cmp_eq_u32 s59, s66
	s_cselect_b32 s95, s65, s35
	s_cselect_b32 s94, s64, s34
	v_add_u32_e32 v0, s89, v217
	s_cselect_b32 s67, s53, s80
	s_cselect_b32 s66, s52, s70
	s_add_i32 vcc_hi, 0, 0x14000
	ds_read_b128 v[132:135], v0
	ds_read_b128 v[136:139], v0 offset:1024
	ds_read_b128 v[140:143], v0 offset:2048
	ds_read_b128 v[144:147], v0 offset:3072
	v_add_u32_e32 v0, vcc_hi, v217
	s_nop 0
	ds_read_b128 v[148:151], v0
	ds_read_b128 v[152:155], v0 offset:1024
	ds_read_b128 v[156:159], v0 offset:2048
	ds_read_b128 v[160:163], v0 offset:3072
	v_add_u32_e32 v0, 0, v216
	s_nop 0
	s_add_i32 m0, s29, 0xc000
	ds_read_b128 v[164:167], v0
	ds_read_b128 v[168:171], v0 offset:1024
	ds_read_b128 v[172:175], v0 offset:2048
	ds_read_b128 v[176:179], v0 offset:3072
	ds_read_b128 v[180:183], v0 offset:4096
	ds_read_b128 v[184:187], v0 offset:5120
	ds_read_b128 v[188:191], v0 offset:6144
	ds_read_b128 v[250:253], v0 offset:7168
	global_load_lds_dwordx4 v204, s[8:9]
	s_add_i32 m0, s29, 0xe000
	s_nop 0
	s_nop 0
	global_load_lds_dwordx4 v206, s[8:9]
	s_waitcnt vmcnt(8) lgkmcnt(0)
	s_barrier
	v_mfma_f32_16x16x32_bf16 v[128:131], v[132:135], v[164:167], v[128:131]
	v_mfma_f32_16x16x32_bf16 v[112:115], v[140:143], v[164:167], v[112:115]
	v_mfma_f32_16x16x32_bf16 v[120:123], v[132:135], v[172:175], v[120:123]
	v_mfma_f32_16x16x32_bf16 v[96:99], v[140:143], v[172:175], v[96:99]
	v_mfma_f32_16x16x32_bf16 v[104:107], v[132:135], v[180:183], v[104:107]
	v_mfma_f32_16x16x32_bf16 v[88:91], v[140:143], v[180:183], v[88:91]
	v_mfma_f32_16x16x32_bf16 v[84:87], v[132:135], v[188:191], v[84:87]
	v_mfma_f32_16x16x32_bf16 v[72:75], v[140:143], v[188:191], v[72:75]
	v_mfma_f32_16x16x32_bf16 v[128:131], v[136:139], v[168:171], v[128:131]
	v_mfma_f32_16x16x32_bf16 v[112:115], v[144:147], v[168:171], v[112:115]
	v_mfma_f32_16x16x32_bf16 v[120:123], v[136:139], v[176:179], v[120:123]
	v_mfma_f32_16x16x32_bf16 v[96:99], v[144:147], v[176:179], v[96:99]
	v_mfma_f32_16x16x32_bf16 v[104:107], v[136:139], v[184:187], v[104:107]
	v_mfma_f32_16x16x32_bf16 v[88:91], v[144:147], v[184:187], v[88:91]
	v_mfma_f32_16x16x32_bf16 v[84:87], v[136:139], v[250:253], v[84:87]
	v_mfma_f32_16x16x32_bf16 v[72:75], v[144:147], v[250:253], v[72:75]
	v_mfma_f32_16x16x32_bf16 v[124:127], v[148:151], v[164:167], v[124:127]
	v_mfma_f32_16x16x32_bf16 v[108:111], v[156:159], v[164:167], v[108:111]
	v_mfma_f32_16x16x32_bf16 v[116:119], v[148:151], v[172:175], v[116:119]
	v_mfma_f32_16x16x32_bf16 v[92:95], v[156:159], v[172:175], v[92:95]
	v_mfma_f32_16x16x32_bf16 v[100:103], v[148:151], v[180:183], v[100:103]
	v_mfma_f32_16x16x32_bf16 v[80:83], v[156:159], v[180:183], v[80:83]
	v_mfma_f32_16x16x32_bf16 v[76:79], v[148:151], v[188:191], v[76:79]
	v_mfma_f32_16x16x32_bf16 v[68:71], v[156:159], v[188:191], v[68:71]
	v_mfma_f32_16x16x32_bf16 v[124:127], v[152:155], v[168:171], v[124:127]
	v_mfma_f32_16x16x32_bf16 v[108:111], v[160:163], v[168:171], v[108:111]
	v_mfma_f32_16x16x32_bf16 v[116:119], v[152:155], v[176:179], v[116:119]
	v_mfma_f32_16x16x32_bf16 v[92:95], v[160:163], v[176:179], v[92:95]
	v_mfma_f32_16x16x32_bf16 v[100:103], v[152:155], v[184:187], v[100:103]
	v_mfma_f32_16x16x32_bf16 v[80:83], v[160:163], v[184:187], v[80:83]
	v_mfma_f32_16x16x32_bf16 v[76:79], v[152:155], v[250:253], v[76:79]
	v_mfma_f32_16x16x32_bf16 v[68:71], v[160:163], v[250:253], v[68:71]
	s_barrier
	s_add_i32 s34, s89, s0
	s_mov_b32 m0, s34
	s_nop 0
	ds_read_b128 v[164:167], v0 offset:16384
	ds_read_b128 v[168:171], v0 offset:17408
	ds_read_b128 v[172:175], v0 offset:18432
	ds_read_b128 v[176:179], v0 offset:19456
	ds_read_b128 v[180:183], v0 offset:20480
	ds_read_b128 v[184:187], v0 offset:21504
	ds_read_b128 v[188:191], v0 offset:22528
	ds_read_b128 v[250:253], v0 offset:23552
	global_load_lds_dwordx4 v196, s[66:67]
	s_add_i32 m0, s34, 0x2000
	s_add_u32 s34, s66, 0x4000
	s_addc_u32 s35, s67, 0
	s_add_i32 s89, vcc_hi, s0
	global_load_lds_dwordx4 v200, s[66:67]
	s_mov_b32 m0, s89
	s_nop 0
	global_load_lds_dwordx4 v196, s[34:35]
	s_add_i32 m0, s89, 0x2000
	s_nop 0
	s_nop 0
	global_load_lds_dwordx4 v200, s[34:35]
	s_mov_b32 m0, s29
	s_nop 0
	global_load_lds_dwordx4 v198, s[94:95]
	s_mov_b32 m0, s45
	s_nop 0
	global_load_lds_dwordx4 v202, s[94:95]
	s_waitcnt vmcnt(8) lgkmcnt(0)
	s_barrier
	v_mfma_f32_16x16x32_bf16 v[64:67], v[132:135], v[164:167], v[64:67]
	v_mfma_f32_16x16x32_bf16 v[56:59], v[140:143], v[164:167], v[56:59]
	v_mfma_f32_16x16x32_bf16 v[48:51], v[132:135], v[172:175], v[48:51]
	v_mfma_f32_16x16x32_bf16 v[40:43], v[140:143], v[172:175], v[40:43]
	v_mfma_f32_16x16x32_bf16 v[30:33], v[132:135], v[180:183], v[30:33]
	v_mfma_f32_16x16x32_bf16 v[26:29], v[140:143], v[180:183], v[26:29]
	v_mfma_f32_16x16x32_bf16 v[14:17], v[132:135], v[188:191], v[14:17]
	v_mfma_f32_16x16x32_bf16 v[10:13], v[140:143], v[188:191], v[10:13]
	v_mfma_f32_16x16x32_bf16 v[64:67], v[136:139], v[168:171], v[64:67]
	v_mfma_f32_16x16x32_bf16 v[56:59], v[144:147], v[168:171], v[56:59]
	v_mfma_f32_16x16x32_bf16 v[48:51], v[136:139], v[176:179], v[48:51]
	v_mfma_f32_16x16x32_bf16 v[40:43], v[144:147], v[176:179], v[40:43]
	v_mfma_f32_16x16x32_bf16 v[30:33], v[136:139], v[184:187], v[30:33]
	v_mfma_f32_16x16x32_bf16 v[26:29], v[144:147], v[184:187], v[26:29]
	v_mfma_f32_16x16x32_bf16 v[14:17], v[136:139], v[250:253], v[14:17]
	v_mfma_f32_16x16x32_bf16 v[10:13], v[144:147], v[250:253], v[10:13]
	v_mfma_f32_16x16x32_bf16 v[60:63], v[148:151], v[164:167], v[60:63]
	v_mfma_f32_16x16x32_bf16 v[52:55], v[156:159], v[164:167], v[52:55]
	v_mfma_f32_16x16x32_bf16 v[44:47], v[148:151], v[172:175], v[44:47]
	v_mfma_f32_16x16x32_bf16 v[36:39], v[156:159], v[172:175], v[36:39]
	v_mfma_f32_16x16x32_bf16 v[22:25], v[148:151], v[180:183], v[22:25]
	v_mfma_f32_16x16x32_bf16 v[18:21], v[156:159], v[180:183], v[18:21]
	v_mfma_f32_16x16x32_bf16 v[6:9], v[148:151], v[188:191], v[6:9]
	v_mfma_f32_16x16x32_bf16 v[2:5], v[156:159], v[188:191], v[2:5]
	v_mfma_f32_16x16x32_bf16 v[60:63], v[152:155], v[168:171], v[60:63]
	v_mfma_f32_16x16x32_bf16 v[52:55], v[160:163], v[168:171], v[52:55]
	v_mfma_f32_16x16x32_bf16 v[44:47], v[152:155], v[176:179], v[44:47]
	v_mfma_f32_16x16x32_bf16 v[36:39], v[160:163], v[176:179], v[36:39]
	v_mfma_f32_16x16x32_bf16 v[22:25], v[152:155], v[184:187], v[22:25]
	v_mfma_f32_16x16x32_bf16 v[18:21], v[160:163], v[184:187], v[18:21]
	v_mfma_f32_16x16x32_bf16 v[6:9], v[152:155], v[250:253], v[6:9]
	v_mfma_f32_16x16x32_bf16 v[2:5], v[160:163], v[250:253], v[2:5]
	s_barrier
	s_nop 0
	s_add_i32 s89, 0, 0x18000
	s_add_i32 vcc_hi, 0, 0x1c000
	v_add_u32_e32 v144, s89, v217
	v_add_u32_e32 v160, vcc_hi, v217
	ds_read_b128 v[132:135], v144
	ds_read_b128 v[136:139], v144 offset:1024
	ds_read_b128 v[140:143], v144 offset:2048
	ds_read_b128 v[144:147], v144 offset:3072
	ds_read_b128 v[148:151], v160
	ds_read_b128 v[152:155], v160 offset:1024
	ds_read_b128 v[156:159], v160 offset:2048
	ds_read_b128 v[160:163], v160 offset:3072
	s_add_u32 s34, s94, 0x100000
	s_addc_u32 s35, s95, 0
	s_mov_b32 m0, s82
	ds_read_b128 v[164:167], v0 offset:32768
	ds_read_b128 v[168:171], v0 offset:33792
	ds_read_b128 v[172:175], v0 offset:34816
	ds_read_b128 v[176:179], v0 offset:35840
	ds_read_b128 v[180:183], v0 offset:36864
	ds_read_b128 v[184:187], v0 offset:37888
	ds_read_b128 v[188:191], v0 offset:38912
	ds_read_b128 v[250:253], v0 offset:39936
	global_load_lds_dwordx4 v198, s[34:35]
	s_mov_b32 m0, s90
	s_nop 0
	global_load_lds_dwordx4 v202, s[34:35]
	s_waitcnt vmcnt(8) lgkmcnt(0)
	s_barrier
	v_mfma_f32_16x16x32_bf16 v[128:131], v[132:135], v[164:167], v[128:131]
	v_mfma_f32_16x16x32_bf16 v[112:115], v[140:143], v[164:167], v[112:115]
	v_mfma_f32_16x16x32_bf16 v[120:123], v[132:135], v[172:175], v[120:123]
	v_mfma_f32_16x16x32_bf16 v[96:99], v[140:143], v[172:175], v[96:99]
	v_mfma_f32_16x16x32_bf16 v[104:107], v[132:135], v[180:183], v[104:107]
	v_mfma_f32_16x16x32_bf16 v[88:91], v[140:143], v[180:183], v[88:91]
	v_mfma_f32_16x16x32_bf16 v[84:87], v[132:135], v[188:191], v[84:87]
	v_mfma_f32_16x16x32_bf16 v[72:75], v[140:143], v[188:191], v[72:75]
	v_mfma_f32_16x16x32_bf16 v[128:131], v[136:139], v[168:171], v[128:131]
	v_mfma_f32_16x16x32_bf16 v[112:115], v[144:147], v[168:171], v[112:115]
	v_mfma_f32_16x16x32_bf16 v[120:123], v[136:139], v[176:179], v[120:123]
	v_mfma_f32_16x16x32_bf16 v[96:99], v[144:147], v[176:179], v[96:99]
	v_mfma_f32_16x16x32_bf16 v[104:107], v[136:139], v[184:187], v[104:107]
	v_mfma_f32_16x16x32_bf16 v[88:91], v[144:147], v[184:187], v[88:91]
	v_mfma_f32_16x16x32_bf16 v[84:87], v[136:139], v[250:253], v[84:87]
	v_mfma_f32_16x16x32_bf16 v[72:75], v[144:147], v[250:253], v[72:75]
	v_mfma_f32_16x16x32_bf16 v[124:127], v[148:151], v[164:167], v[124:127]
	v_mfma_f32_16x16x32_bf16 v[108:111], v[156:159], v[164:167], v[108:111]
	v_mfma_f32_16x16x32_bf16 v[116:119], v[148:151], v[172:175], v[116:119]
	v_mfma_f32_16x16x32_bf16 v[92:95], v[156:159], v[172:175], v[92:95]
	v_mfma_f32_16x16x32_bf16 v[100:103], v[148:151], v[180:183], v[100:103]
	v_mfma_f32_16x16x32_bf16 v[80:83], v[156:159], v[180:183], v[80:83]
	v_mfma_f32_16x16x32_bf16 v[76:79], v[148:151], v[188:191], v[76:79]
	v_mfma_f32_16x16x32_bf16 v[68:71], v[156:159], v[188:191], v[68:71]
	v_mfma_f32_16x16x32_bf16 v[124:127], v[152:155], v[168:171], v[124:127]
	v_mfma_f32_16x16x32_bf16 v[108:111], v[160:163], v[168:171], v[108:111]
	v_mfma_f32_16x16x32_bf16 v[116:119], v[152:155], v[176:179], v[116:119]
	v_mfma_f32_16x16x32_bf16 v[92:95], v[160:163], v[176:179], v[92:95]
	v_mfma_f32_16x16x32_bf16 v[100:103], v[152:155], v[184:187], v[100:103]
	v_mfma_f32_16x16x32_bf16 v[80:83], v[160:163], v[184:187], v[80:83]
	v_mfma_f32_16x16x32_bf16 v[76:79], v[152:155], v[250:253], v[76:79]
	v_mfma_f32_16x16x32_bf16 v[68:71], v[160:163], v[250:253], v[68:71]
	s_barrier
	s_nop 0
	s_add_u32 s34, s66, 0x8000
	s_addc_u32 s35, s67, 0
	s_add_i32 s89, s89, s0
	s_mov_b32 m0, s89
	s_nop 0
	ds_read_b128 v[164:167], v0 offset:49152
	ds_read_b128 v[168:171], v0 offset:50176
	ds_read_b128 v[172:175], v0 offset:51200
	ds_read_b128 v[176:179], v0 offset:52224
	ds_read_b128 v[180:183], v0 offset:53248
	ds_read_b128 v[184:187], v0 offset:54272
	ds_read_b128 v[188:191], v0 offset:55296
	ds_read_b128 v[250:253], v0 offset:56320
	global_load_lds_dwordx4 v196, s[34:35]
	s_add_i32 m0, s89, 0x2000
	v_lshl_add_u64 v[210:211], s[34:35], 0, v[200:201]
	s_add_u32 s34, s66, 0xc000
	s_addc_u32 s35, s67, 0
	s_add_i32 s66, vcc_hi, s0
	global_load_lds_dwordx4 v[210:211], off
	s_mov_b32 m0, s66
	s_nop 0
	global_load_lds_dwordx4 v196, s[34:35]
	s_add_i32 m0, s66, 0x2000
	s_nop 0
	s_nop 0
	global_load_lds_dwordx4 v200, s[34:35]
	s_mov_b32 m0, s91
	s_nop 0
	s_add_u32 s100, s94, s92
	s_addc_u32 s101, s95, s93
	global_load_lds_dwordx4 v198, s[100:101]
	s_mov_b32 m0, s30
	s_nop 0
	s_add_u32 s100, s94, s92
	s_addc_u32 s101, s95, s93
	global_load_lds_dwordx4 v202, s[100:101]
	s_waitcnt vmcnt(8) lgkmcnt(0)
	s_barrier
	v_mfma_f32_16x16x32_bf16 v[64:67], v[132:135], v[164:167], v[64:67]
	v_mfma_f32_16x16x32_bf16 v[56:59], v[140:143], v[164:167], v[56:59]
	v_mfma_f32_16x16x32_bf16 v[48:51], v[132:135], v[172:175], v[48:51]
	v_mfma_f32_16x16x32_bf16 v[40:43], v[140:143], v[172:175], v[40:43]
	v_mfma_f32_16x16x32_bf16 v[30:33], v[132:135], v[180:183], v[30:33]
	v_mfma_f32_16x16x32_bf16 v[26:29], v[140:143], v[180:183], v[26:29]
	v_mfma_f32_16x16x32_bf16 v[14:17], v[132:135], v[188:191], v[14:17]
	v_mfma_f32_16x16x32_bf16 v[10:13], v[140:143], v[188:191], v[10:13]
	v_mfma_f32_16x16x32_bf16 v[64:67], v[136:139], v[168:171], v[64:67]
	v_mfma_f32_16x16x32_bf16 v[56:59], v[144:147], v[168:171], v[56:59]
	v_mfma_f32_16x16x32_bf16 v[48:51], v[136:139], v[176:179], v[48:51]
	v_mfma_f32_16x16x32_bf16 v[40:43], v[144:147], v[176:179], v[40:43]
	v_mfma_f32_16x16x32_bf16 v[30:33], v[136:139], v[184:187], v[30:33]
	v_mfma_f32_16x16x32_bf16 v[26:29], v[144:147], v[184:187], v[26:29]
	v_mfma_f32_16x16x32_bf16 v[14:17], v[136:139], v[250:253], v[14:17]
	v_mfma_f32_16x16x32_bf16 v[10:13], v[144:147], v[250:253], v[10:13]
	v_mfma_f32_16x16x32_bf16 v[60:63], v[148:151], v[164:167], v[60:63]
	v_mfma_f32_16x16x32_bf16 v[52:55], v[156:159], v[164:167], v[52:55]
	v_mfma_f32_16x16x32_bf16 v[44:47], v[148:151], v[172:175], v[44:47]
	v_mfma_f32_16x16x32_bf16 v[36:39], v[156:159], v[172:175], v[36:39]
	v_mfma_f32_16x16x32_bf16 v[22:25], v[148:151], v[180:183], v[22:25]
	v_mfma_f32_16x16x32_bf16 v[18:21], v[156:159], v[180:183], v[18:21]
	v_mfma_f32_16x16x32_bf16 v[6:9], v[148:151], v[188:191], v[6:9]
	v_mfma_f32_16x16x32_bf16 v[2:5], v[156:159], v[188:191], v[2:5]
	v_mfma_f32_16x16x32_bf16 v[60:63], v[152:155], v[168:171], v[60:63]
	v_mfma_f32_16x16x32_bf16 v[52:55], v[160:163], v[168:171], v[52:55]
	v_mfma_f32_16x16x32_bf16 v[44:47], v[152:155], v[176:179], v[44:47]
	v_mfma_f32_16x16x32_bf16 v[36:39], v[160:163], v[176:179], v[36:39]
	v_mfma_f32_16x16x32_bf16 v[22:25], v[152:155], v[184:187], v[22:25]
	v_mfma_f32_16x16x32_bf16 v[18:21], v[160:163], v[184:187], v[18:21]
	v_mfma_f32_16x16x32_bf16 v[6:9], v[152:155], v[250:253], v[6:9]
	v_mfma_f32_16x16x32_bf16 v[2:5], v[160:163], v[250:253], v[2:5]
	s_barrier
	s_nop 0
	s_add_u32 s70, s70, 0x10000
	s_addc_u32 s80, s80, 0
	s_nop 0
	s_add_u32 s8, s8, 0x100
	s_addc_u32 s9, s9, 0
	s_cmp_lt_i32 vcc_lo, s58
	s_mov_b32 s66, vcc_lo
	s_cbranch_scc1 .LBB0_324
	s_nop 0
	s_nop 0
	s_nop 0
	s_nop 0
	v_mov_b32_e32 v252, v212
	s_branch .LBB0_235

.LBB0_327:
	s_add_i32 s70, s8, 2
	s_nop 0
	s_add_u32 s9, s6, 0xfff00080
	s_addc_u32 s10, s7, -1
	s_nop 0
	s_add_i32 s34, 0, 0x10000
	s_cmp_eq_u32 s59, s8
	s_cselect_b32 s11, s65, s10
	s_cselect_b32 s10, s64, s9
	v_add_u32_e32 v0, s34, v217
	s_cselect_b32 s9, s53, s67
	s_cselect_b32 s8, s52, s66
	s_add_i32 s35, 0, 0x14000
	ds_read_b128 v[132:135], v0
	ds_read_b128 v[136:139], v0 offset:1024
	ds_read_b128 v[140:143], v0 offset:2048
	ds_read_b128 v[144:147], v0 offset:3072
	v_add_u32_e32 v0, s35, v217
	s_nop 0
	ds_read_b128 v[148:151], v0
	ds_read_b128 v[152:155], v0 offset:1024
	ds_read_b128 v[156:159], v0 offset:2048
	ds_read_b128 v[160:163], v0 offset:3072
	v_add_u32_e32 v0, 0, v216
	s_nop 0
	s_add_i32 m0, s29, 0xc000
	ds_read_b128 v[164:167], v0
	ds_read_b128 v[168:171], v0 offset:1024
	ds_read_b128 v[172:175], v0 offset:2048
	ds_read_b128 v[176:179], v0 offset:3072
	ds_read_b128 v[180:183], v0 offset:4096
	ds_read_b128 v[184:187], v0 offset:5120
	ds_read_b128 v[188:191], v0 offset:6144
	ds_read_b128 v[250:253], v0 offset:7168
	global_load_lds_dwordx4 v204, s[6:7]
	s_add_i32 m0, s29, 0xe000
	s_nop 0
	s_nop 0
	global_load_lds_dwordx4 v206, s[6:7]
	s_waitcnt vmcnt(8) lgkmcnt(0)
	s_barrier
	v_mfma_i32_16x16x64_i8 v[128:131], v[132:135], v[164:167], v[128:131]
	v_mfma_i32_16x16x64_i8 v[112:115], v[140:143], v[164:167], v[112:115]
	v_mfma_i32_16x16x64_i8 v[120:123], v[132:135], v[172:175], v[120:123]
	v_mfma_i32_16x16x64_i8 v[96:99], v[140:143], v[172:175], v[96:99]
	v_mfma_i32_16x16x64_i8 v[104:107], v[132:135], v[180:183], v[104:107]
	v_mfma_i32_16x16x64_i8 v[88:91], v[140:143], v[180:183], v[88:91]
	v_mfma_i32_16x16x64_i8 v[84:87], v[132:135], v[188:191], v[84:87]
	v_mfma_i32_16x16x64_i8 v[72:75], v[140:143], v[188:191], v[72:75]
	v_mfma_i32_16x16x64_i8 v[128:131], v[136:139], v[168:171], v[128:131]
	v_mfma_i32_16x16x64_i8 v[112:115], v[144:147], v[168:171], v[112:115]
	v_mfma_i32_16x16x64_i8 v[120:123], v[136:139], v[176:179], v[120:123]
	v_mfma_i32_16x16x64_i8 v[96:99], v[144:147], v[176:179], v[96:99]
	v_mfma_i32_16x16x64_i8 v[104:107], v[136:139], v[184:187], v[104:107]
	v_mfma_i32_16x16x64_i8 v[88:91], v[144:147], v[184:187], v[88:91]
	v_mfma_i32_16x16x64_i8 v[84:87], v[136:139], v[250:253], v[84:87]
	v_mfma_i32_16x16x64_i8 v[72:75], v[144:147], v[250:253], v[72:75]
	v_mfma_i32_16x16x64_i8 v[124:127], v[148:151], v[164:167], v[124:127]
	v_mfma_i32_16x16x64_i8 v[108:111], v[156:159], v[164:167], v[108:111]
	v_mfma_i32_16x16x64_i8 v[116:119], v[148:151], v[172:175], v[116:119]
	v_mfma_i32_16x16x64_i8 v[92:95], v[156:159], v[172:175], v[92:95]
	v_mfma_i32_16x16x64_i8 v[100:103], v[148:151], v[180:183], v[100:103]
	v_mfma_i32_16x16x64_i8 v[80:83], v[156:159], v[180:183], v[80:83]
	v_mfma_i32_16x16x64_i8 v[76:79], v[148:151], v[188:191], v[76:79]
	v_mfma_i32_16x16x64_i8 v[68:71], v[156:159], v[188:191], v[68:71]
	v_mfma_i32_16x16x64_i8 v[124:127], v[152:155], v[168:171], v[124:127]
	v_mfma_i32_16x16x64_i8 v[108:111], v[160:163], v[168:171], v[108:111]
	v_mfma_i32_16x16x64_i8 v[116:119], v[152:155], v[176:179], v[116:119]
	v_mfma_i32_16x16x64_i8 v[92:95], v[160:163], v[176:179], v[92:95]
	v_mfma_i32_16x16x64_i8 v[100:103], v[152:155], v[184:187], v[100:103]
	v_mfma_i32_16x16x64_i8 v[80:83], v[160:163], v[184:187], v[80:83]
	v_mfma_i32_16x16x64_i8 v[76:79], v[152:155], v[250:253], v[76:79]
	v_mfma_i32_16x16x64_i8 v[68:71], v[160:163], v[250:253], v[68:71]
	s_barrier
	s_add_i32 s34, s34, s0
	s_mov_b32 m0, s34
	s_nop 0
	ds_read_b128 v[164:167], v0 offset:16384
	ds_read_b128 v[168:171], v0 offset:17408
	ds_read_b128 v[172:175], v0 offset:18432
	ds_read_b128 v[176:179], v0 offset:19456
	ds_read_b128 v[180:183], v0 offset:20480
	ds_read_b128 v[184:187], v0 offset:21504
	ds_read_b128 v[188:191], v0 offset:22528
	ds_read_b128 v[250:253], v0 offset:23552
	global_load_lds_dwordx4 v196, s[8:9]
	s_add_i32 m0, s34, 0x2000
	s_add_u32 s94, s8, 0x4000
	s_addc_u32 s95, s9, 0
	s_add_i32 s34, s35, s0
	global_load_lds_dwordx4 v200, s[8:9]
	s_mov_b32 m0, s34
	s_nop 0
	v_lshl_add_u64 v[194:195], s[10:11], 0, v[202:203]
	global_load_lds_dwordx4 v196, s[94:95]
	s_add_i32 m0, s34, 0x2000
	s_nop 0
	s_nop 0
	global_load_lds_dwordx4 v200, s[94:95]
	v_lshl_add_u64 v[192:193], s[10:11], 0, v[198:199]
	s_mov_b32 m0, s29
	s_nop 0
	global_load_lds_dwordx4 v198, s[10:11]
	s_mov_b32 m0, s45
	s_nop 0
	global_load_lds_dwordx4 v202, s[10:11]
	s_waitcnt vmcnt(8) lgkmcnt(0)
	s_barrier
	v_mfma_i32_16x16x64_i8 v[64:67], v[132:135], v[164:167], v[64:67]
	v_mfma_i32_16x16x64_i8 v[56:59], v[140:143], v[164:167], v[56:59]
	v_mfma_i32_16x16x64_i8 v[48:51], v[132:135], v[172:175], v[48:51]
	v_mfma_i32_16x16x64_i8 v[40:43], v[140:143], v[172:175], v[40:43]
	v_mfma_i32_16x16x64_i8 v[30:33], v[132:135], v[180:183], v[30:33]
	v_mfma_i32_16x16x64_i8 v[26:29], v[140:143], v[180:183], v[26:29]
	v_mfma_i32_16x16x64_i8 v[14:17], v[132:135], v[188:191], v[14:17]
	v_mfma_i32_16x16x64_i8 v[10:13], v[140:143], v[188:191], v[10:13]
	v_mfma_i32_16x16x64_i8 v[64:67], v[136:139], v[168:171], v[64:67]
	v_mfma_i32_16x16x64_i8 v[56:59], v[144:147], v[168:171], v[56:59]
	v_mfma_i32_16x16x64_i8 v[48:51], v[136:139], v[176:179], v[48:51]
	v_mfma_i32_16x16x64_i8 v[40:43], v[144:147], v[176:179], v[40:43]
	v_mfma_i32_16x16x64_i8 v[30:33], v[136:139], v[184:187], v[30:33]
	v_mfma_i32_16x16x64_i8 v[26:29], v[144:147], v[184:187], v[26:29]
	v_mfma_i32_16x16x64_i8 v[14:17], v[136:139], v[250:253], v[14:17]
	v_mfma_i32_16x16x64_i8 v[10:13], v[144:147], v[250:253], v[10:13]
	v_mfma_i32_16x16x64_i8 v[60:63], v[148:151], v[164:167], v[60:63]
	v_mfma_i32_16x16x64_i8 v[52:55], v[156:159], v[164:167], v[52:55]
	v_mfma_i32_16x16x64_i8 v[44:47], v[148:151], v[172:175], v[44:47]
	v_mfma_i32_16x16x64_i8 v[36:39], v[156:159], v[172:175], v[36:39]
	v_mfma_i32_16x16x64_i8 v[22:25], v[148:151], v[180:183], v[22:25]
	v_mfma_i32_16x16x64_i8 v[18:21], v[156:159], v[180:183], v[18:21]
	v_mfma_i32_16x16x64_i8 v[6:9], v[148:151], v[188:191], v[6:9]
	v_mfma_i32_16x16x64_i8 v[2:5], v[156:159], v[188:191], v[2:5]
	v_mfma_i32_16x16x64_i8 v[60:63], v[152:155], v[168:171], v[60:63]
	v_mfma_i32_16x16x64_i8 v[52:55], v[160:163], v[168:171], v[52:55]
	v_mfma_i32_16x16x64_i8 v[44:47], v[152:155], v[176:179], v[44:47]
	v_mfma_i32_16x16x64_i8 v[36:39], v[160:163], v[176:179], v[36:39]
	v_mfma_i32_16x16x64_i8 v[22:25], v[152:155], v[184:187], v[22:25]
	v_mfma_i32_16x16x64_i8 v[18:21], v[160:163], v[184:187], v[18:21]
	v_mfma_i32_16x16x64_i8 v[6:9], v[152:155], v[250:253], v[6:9]
	v_mfma_i32_16x16x64_i8 v[2:5], v[160:163], v[250:253], v[2:5]
	s_barrier
	s_nop 0
	s_add_i32 s34, 0, 0x18000
	s_add_i32 s35, 0, 0x1c000
	v_add_u32_e32 v144, s34, v217
	v_add_u32_e32 v160, s35, v217
	ds_read_b128 v[132:135], v144
	ds_read_b128 v[136:139], v144 offset:1024
	ds_read_b128 v[140:143], v144 offset:2048
	ds_read_b128 v[144:147], v144 offset:3072
	ds_read_b128 v[148:151], v160
	ds_read_b128 v[152:155], v160 offset:1024
	ds_read_b128 v[156:159], v160 offset:2048
	ds_read_b128 v[160:163], v160 offset:3072
	s_add_u32 s10, s10, 0x100000
	s_addc_u32 s11, s11, 0
	s_mov_b32 m0, s82
	ds_read_b128 v[164:167], v0 offset:32768
	ds_read_b128 v[168:171], v0 offset:33792
	ds_read_b128 v[172:175], v0 offset:34816
	ds_read_b128 v[176:179], v0 offset:35840
	ds_read_b128 v[180:183], v0 offset:36864
	ds_read_b128 v[184:187], v0 offset:37888
	ds_read_b128 v[188:191], v0 offset:38912
	ds_read_b128 v[250:253], v0 offset:39936
	global_load_lds_dwordx4 v198, s[10:11]
	s_mov_b32 m0, s90
	s_nop 0
	global_load_lds_dwordx4 v202, s[10:11]
	s_waitcnt vmcnt(8) lgkmcnt(0)
	s_barrier
	v_mfma_i32_16x16x64_i8 v[128:131], v[132:135], v[164:167], v[128:131]
	v_mfma_i32_16x16x64_i8 v[112:115], v[140:143], v[164:167], v[112:115]
	v_mfma_i32_16x16x64_i8 v[120:123], v[132:135], v[172:175], v[120:123]
	v_mfma_i32_16x16x64_i8 v[96:99], v[140:143], v[172:175], v[96:99]
	v_mfma_i32_16x16x64_i8 v[104:107], v[132:135], v[180:183], v[104:107]
	v_mfma_i32_16x16x64_i8 v[88:91], v[140:143], v[180:183], v[88:91]
	v_mfma_i32_16x16x64_i8 v[84:87], v[132:135], v[188:191], v[84:87]
	v_mfma_i32_16x16x64_i8 v[72:75], v[140:143], v[188:191], v[72:75]
	v_mfma_i32_16x16x64_i8 v[128:131], v[136:139], v[168:171], v[128:131]
	v_mfma_i32_16x16x64_i8 v[112:115], v[144:147], v[168:171], v[112:115]
	v_mfma_i32_16x16x64_i8 v[120:123], v[136:139], v[176:179], v[120:123]
	v_mfma_i32_16x16x64_i8 v[96:99], v[144:147], v[176:179], v[96:99]
	v_mfma_i32_16x16x64_i8 v[104:107], v[136:139], v[184:187], v[104:107]
	v_mfma_i32_16x16x64_i8 v[88:91], v[144:147], v[184:187], v[88:91]
	v_mfma_i32_16x16x64_i8 v[84:87], v[136:139], v[250:253], v[84:87]
	v_mfma_i32_16x16x64_i8 v[72:75], v[144:147], v[250:253], v[72:75]
	v_mfma_i32_16x16x64_i8 v[124:127], v[148:151], v[164:167], v[124:127]
	v_mfma_i32_16x16x64_i8 v[108:111], v[156:159], v[164:167], v[108:111]
	v_mfma_i32_16x16x64_i8 v[116:119], v[148:151], v[172:175], v[116:119]
	v_mfma_i32_16x16x64_i8 v[92:95], v[156:159], v[172:175], v[92:95]
	v_mfma_i32_16x16x64_i8 v[100:103], v[148:151], v[180:183], v[100:103]
	v_mfma_i32_16x16x64_i8 v[80:83], v[156:159], v[180:183], v[80:83]
	v_mfma_i32_16x16x64_i8 v[76:79], v[148:151], v[188:191], v[76:79]
	v_mfma_i32_16x16x64_i8 v[68:71], v[156:159], v[188:191], v[68:71]
	v_mfma_i32_16x16x64_i8 v[124:127], v[152:155], v[168:171], v[124:127]
	v_mfma_i32_16x16x64_i8 v[108:111], v[160:163], v[168:171], v[108:111]
	v_mfma_i32_16x16x64_i8 v[116:119], v[152:155], v[176:179], v[116:119]
	v_mfma_i32_16x16x64_i8 v[92:95], v[160:163], v[176:179], v[92:95]
	v_mfma_i32_16x16x64_i8 v[100:103], v[152:155], v[184:187], v[100:103]
	v_mfma_i32_16x16x64_i8 v[80:83], v[160:163], v[184:187], v[80:83]
	v_mfma_i32_16x16x64_i8 v[76:79], v[152:155], v[250:253], v[76:79]
	v_mfma_i32_16x16x64_i8 v[68:71], v[160:163], v[250:253], v[68:71]
	s_barrier
	s_nop 0
	s_add_u32 s10, s8, 0x8000
	s_addc_u32 s11, s9, 0
	s_add_i32 s34, s34, s0
	s_mov_b32 m0, s34
	s_nop 0
	ds_read_b128 v[164:167], v0 offset:49152
	ds_read_b128 v[168:171], v0 offset:50176
	ds_read_b128 v[172:175], v0 offset:51200
	ds_read_b128 v[176:179], v0 offset:52224
	ds_read_b128 v[180:183], v0 offset:53248
	ds_read_b128 v[184:187], v0 offset:54272
	ds_read_b128 v[188:191], v0 offset:55296
	ds_read_b128 v[250:253], v0 offset:56320
	global_load_lds_dwordx4 v196, s[10:11]
	s_add_i32 m0, s34, 0x2000
	s_add_u32 s8, s8, 0xc000
	v_lshl_add_u64 v[210:211], s[10:11], 0, v[200:201]
	s_addc_u32 s9, s9, 0
	s_add_i32 s10, s35, s0
	global_load_lds_dwordx4 v[210:211], off
	s_mov_b32 m0, s10
	s_nop 0
	v_lshl_add_u64 v[192:193], v[192:193], 0, s[92:93]
	global_load_lds_dwordx4 v196, s[8:9]
	s_add_i32 m0, s10, 0x2000
	s_nop 0
	s_nop 0
	global_load_lds_dwordx4 v200, s[8:9]
	s_mov_b32 m0, s91
	s_nop 0
	global_load_lds_dwordx4 v[192:193], off
	v_lshl_add_u64 v[192:193], v[194:195], 0, s[92:93]
	s_mov_b32 m0, s30
	s_nop 0
	global_load_lds_dwordx4 v[192:193], off
	s_waitcnt vmcnt(8) lgkmcnt(0)
	s_barrier
	v_mfma_i32_16x16x64_i8 v[64:67], v[132:135], v[164:167], v[64:67]
	v_mfma_i32_16x16x64_i8 v[56:59], v[140:143], v[164:167], v[56:59]
	v_mfma_i32_16x16x64_i8 v[48:51], v[132:135], v[172:175], v[48:51]
	v_mfma_i32_16x16x64_i8 v[40:43], v[140:143], v[172:175], v[40:43]
	v_mfma_i32_16x16x64_i8 v[30:33], v[132:135], v[180:183], v[30:33]
	v_mfma_i32_16x16x64_i8 v[26:29], v[140:143], v[180:183], v[26:29]
	v_mfma_i32_16x16x64_i8 v[14:17], v[132:135], v[188:191], v[14:17]
	v_mfma_i32_16x16x64_i8 v[10:13], v[140:143], v[188:191], v[10:13]
	v_mfma_i32_16x16x64_i8 v[64:67], v[136:139], v[168:171], v[64:67]
	v_mfma_i32_16x16x64_i8 v[56:59], v[144:147], v[168:171], v[56:59]
	v_mfma_i32_16x16x64_i8 v[48:51], v[136:139], v[176:179], v[48:51]
	v_mfma_i32_16x16x64_i8 v[40:43], v[144:147], v[176:179], v[40:43]
	v_mfma_i32_16x16x64_i8 v[30:33], v[136:139], v[184:187], v[30:33]
	v_mfma_i32_16x16x64_i8 v[26:29], v[144:147], v[184:187], v[26:29]
	v_mfma_i32_16x16x64_i8 v[14:17], v[136:139], v[250:253], v[14:17]
	v_mfma_i32_16x16x64_i8 v[10:13], v[144:147], v[250:253], v[10:13]
	v_mfma_i32_16x16x64_i8 v[60:63], v[148:151], v[164:167], v[60:63]
	v_mfma_i32_16x16x64_i8 v[52:55], v[156:159], v[164:167], v[52:55]
	v_mfma_i32_16x16x64_i8 v[44:47], v[148:151], v[172:175], v[44:47]
	v_mfma_i32_16x16x64_i8 v[36:39], v[156:159], v[172:175], v[36:39]
	v_mfma_i32_16x16x64_i8 v[22:25], v[148:151], v[180:183], v[22:25]
	v_mfma_i32_16x16x64_i8 v[18:21], v[156:159], v[180:183], v[18:21]
	v_mfma_i32_16x16x64_i8 v[6:9], v[148:151], v[188:191], v[6:9]
	v_mfma_i32_16x16x64_i8 v[2:5], v[156:159], v[188:191], v[2:5]
	v_mfma_i32_16x16x64_i8 v[60:63], v[152:155], v[168:171], v[60:63]
	v_mfma_i32_16x16x64_i8 v[52:55], v[160:163], v[168:171], v[52:55]
	v_mfma_i32_16x16x64_i8 v[44:47], v[152:155], v[176:179], v[44:47]
	v_mfma_i32_16x16x64_i8 v[36:39], v[160:163], v[176:179], v[36:39]
	v_mfma_i32_16x16x64_i8 v[22:25], v[152:155], v[184:187], v[22:25]
	v_mfma_i32_16x16x64_i8 v[18:21], v[160:163], v[184:187], v[18:21]
	v_mfma_i32_16x16x64_i8 v[6:9], v[152:155], v[250:253], v[6:9]
	v_mfma_i32_16x16x64_i8 v[2:5], v[160:163], v[250:253], v[2:5]
	s_barrier
	s_nop 0
	s_add_u32 s66, s66, 0x10000
	s_addc_u32 s67, s67, 0
	s_nop 0
	s_add_u32 s6, s6, 0x100
	s_addc_u32 s7, s7, 0
	s_cmp_ge_i32 s70, s58
	s_mov_b32 s8, s70
	s_cbranch_scc0 .LBB0_327
	s_nop 0
	v_mov_b32_e32 v252, v212
	v_cndmask_b32_e64 v0, 0, 1, s[46:47]
	v_cmp_ne_u32_e64 s[6:7], 1, v0
	s_andn2_b64 vcc, exec, s[46:47]
	s_cbranch_vccz .LBB0_236
	s_branch .LBB0_237

.LBB0_707:
	s_add_u32 s34, s50, 0xfff80080
	s_addc_u32 s35, s51, -1
	s_nop 0
	s_add_i32 s61, 0, 0x10000
	s_cmp_eq_u32 s60, 4
	s_cselect_b32 s55, s23, s35
	s_cselect_b32 s54, s22, s34
	s_cselect_b32 s53, s43, s59
	s_cselect_b32 s52, s42, s21
	s_nop 0
	s_add_i32 s62, 0, 0x14000
	ds_read_b128 v[164:167], v2 offset:0
	ds_read_b128 v[168:171], v2 offset:1024
	ds_read_b128 v[172:175], v2 offset:2048
	ds_read_b128 v[176:179], v2 offset:3072
	ds_read_b128 v[192:195], v2 offset:16384
	ds_read_b128 v[196:199], v2 offset:17408
	ds_read_b128 v[204:207], v2 offset:18432
	ds_read_b128 v[210:213], v2 offset:19456
	s_add_i32 m0, s29, 0xc000
	ds_read_b128 v[216:219], v203
	ds_read_b128 v[220:223], v203 offset:1024
	ds_read_b128 v[224:227], v203 offset:2048
	ds_read_b128 v[228:231], v203 offset:3072
	ds_read_b128 v[232:235], v203 offset:4096
	ds_read_b128 v[236:239], v203 offset:5120
	ds_read_b128 v[240:243], v203 offset:6144
	ds_read_b128 v[244:247], v203 offset:7168
	global_load_lds_dwordx4 v188, s[50:51]
	s_add_i32 m0, s29, 0xe000
	s_nop 0
	s_nop 0
	global_load_lds_dwordx4 v190, s[50:51]
	s_waitcnt vmcnt(8) lgkmcnt(0)
	s_barrier
	v_mfma_f32_16x16x32_bf16 v[160:163], v[164:167], v[216:219], v[160:163]
	v_mfma_f32_16x16x32_bf16 v[156:159], v[172:175], v[216:219], v[156:159]
	v_mfma_f32_16x16x32_bf16 v[144:147], v[164:167], v[224:227], v[144:147]
	v_mfma_f32_16x16x32_bf16 v[140:143], v[172:175], v[224:227], v[140:143]
	v_mfma_f32_16x16x32_bf16 v[128:131], v[164:167], v[232:235], v[128:131]
	v_mfma_f32_16x16x32_bf16 v[124:127], v[172:175], v[232:235], v[124:127]
	v_mfma_f32_16x16x32_bf16 v[112:115], v[164:167], v[240:243], v[112:115]
	v_mfma_f32_16x16x32_bf16 v[108:111], v[172:175], v[240:243], v[108:111]
	v_mfma_f32_16x16x32_bf16 v[160:163], v[168:171], v[220:223], v[160:163]
	v_mfma_f32_16x16x32_bf16 v[156:159], v[176:179], v[220:223], v[156:159]
	v_mfma_f32_16x16x32_bf16 v[144:147], v[168:171], v[228:231], v[144:147]
	v_mfma_f32_16x16x32_bf16 v[140:143], v[176:179], v[228:231], v[140:143]
	v_mfma_f32_16x16x32_bf16 v[128:131], v[168:171], v[236:239], v[128:131]
	v_mfma_f32_16x16x32_bf16 v[124:127], v[176:179], v[236:239], v[124:127]
	v_mfma_f32_16x16x32_bf16 v[112:115], v[168:171], v[244:247], v[112:115]
	v_mfma_f32_16x16x32_bf16 v[108:111], v[176:179], v[244:247], v[108:111]
	v_mfma_f32_16x16x32_bf16 v[152:155], v[192:195], v[216:219], v[152:155]
	v_mfma_f32_16x16x32_bf16 v[148:151], v[204:207], v[216:219], v[148:151]
	v_mfma_f32_16x16x32_bf16 v[136:139], v[192:195], v[224:227], v[136:139]
	v_mfma_f32_16x16x32_bf16 v[132:135], v[204:207], v[224:227], v[132:135]
	v_mfma_f32_16x16x32_bf16 v[120:123], v[192:195], v[232:235], v[120:123]
	v_mfma_f32_16x16x32_bf16 v[116:119], v[204:207], v[232:235], v[116:119]
	v_mfma_f32_16x16x32_bf16 v[104:107], v[192:195], v[240:243], v[104:107]
	v_mfma_f32_16x16x32_bf16 v[100:103], v[204:207], v[240:243], v[100:103]
	v_mfma_f32_16x16x32_bf16 v[152:155], v[196:199], v[220:223], v[152:155]
	v_mfma_f32_16x16x32_bf16 v[148:151], v[210:213], v[220:223], v[148:151]
	v_mfma_f32_16x16x32_bf16 v[136:139], v[196:199], v[228:231], v[136:139]
	v_mfma_f32_16x16x32_bf16 v[132:135], v[210:213], v[228:231], v[132:135]
	v_mfma_f32_16x16x32_bf16 v[120:123], v[196:199], v[236:239], v[120:123]
	v_mfma_f32_16x16x32_bf16 v[116:119], v[210:213], v[236:239], v[116:119]
	v_mfma_f32_16x16x32_bf16 v[104:107], v[196:199], v[244:247], v[104:107]
	v_mfma_f32_16x16x32_bf16 v[100:103], v[210:213], v[244:247], v[100:103]
	s_barrier
	s_add_i32 s34, s61, s0
	s_mov_b32 m0, s34
	s_nop 0
	ds_read_b128 v[216:219], v203 offset:16384
	ds_read_b128 v[220:223], v203 offset:17408
	ds_read_b128 v[224:227], v203 offset:18432
	ds_read_b128 v[228:231], v203 offset:19456
	ds_read_b128 v[232:235], v203 offset:20480
	ds_read_b128 v[236:239], v203 offset:21504
	ds_read_b128 v[240:243], v203 offset:22528
	ds_read_b128 v[244:247], v203 offset:23552
	global_load_lds_dwordx4 v180, s[52:53]
	s_add_i32 m0, s34, 0x2000
	s_add_u32 s34, s52, 0x4000
	s_addc_u32 s35, s53, 0
	s_add_i32 s61, s62, s0
	global_load_lds_dwordx4 v184, s[52:53]
	s_mov_b32 m0, s61
	s_nop 0
	v_lshl_add_u64 v[248:249], s[54:55], 0, v[186:187]
	global_load_lds_dwordx4 v180, s[34:35]
	s_add_i32 m0, s61, 0x2000
	s_nop 0
	s_nop 0
	global_load_lds_dwordx4 v184, s[34:35]
	v_lshl_add_u64 v[200:201], s[54:55], 0, v[182:183]
	s_mov_b32 m0, s29
	s_nop 0
	global_load_lds_dwordx4 v182, s[54:55]
	s_mov_b32 m0, s45
	s_nop 0
	global_load_lds_dwordx4 v186, s[54:55]
	s_waitcnt vmcnt(8) lgkmcnt(0)
	s_barrier
	v_mfma_f32_16x16x32_bf16 v[96:99], v[164:167], v[216:219], v[96:99]
	v_mfma_f32_16x16x32_bf16 v[92:95], v[172:175], v[216:219], v[92:95]
	v_mfma_f32_16x16x32_bf16 v[84:87], v[164:167], v[224:227], v[84:87]
	v_mfma_f32_16x16x32_bf16 v[76:79], v[172:175], v[224:227], v[76:79]
	v_mfma_f32_16x16x32_bf16 v[68:71], v[164:167], v[232:235], v[68:71]
	v_mfma_f32_16x16x32_bf16 v[60:63], v[172:175], v[232:235], v[60:63]
	v_mfma_f32_16x16x32_bf16 v[52:55], v[164:167], v[240:243], v[52:55]
	v_mfma_f32_16x16x32_bf16 v[44:47], v[172:175], v[240:243], v[44:47]
	v_mfma_f32_16x16x32_bf16 v[96:99], v[168:171], v[220:223], v[96:99]
	v_mfma_f32_16x16x32_bf16 v[92:95], v[176:179], v[220:223], v[92:95]
	v_mfma_f32_16x16x32_bf16 v[84:87], v[168:171], v[228:231], v[84:87]
	v_mfma_f32_16x16x32_bf16 v[76:79], v[176:179], v[228:231], v[76:79]
	v_mfma_f32_16x16x32_bf16 v[68:71], v[168:171], v[236:239], v[68:71]
	v_mfma_f32_16x16x32_bf16 v[60:63], v[176:179], v[236:239], v[60:63]
	v_mfma_f32_16x16x32_bf16 v[52:55], v[168:171], v[244:247], v[52:55]
	v_mfma_f32_16x16x32_bf16 v[44:47], v[176:179], v[244:247], v[44:47]
	v_mfma_f32_16x16x32_bf16 v[88:91], v[192:195], v[216:219], v[88:91]
	v_mfma_f32_16x16x32_bf16 v[80:83], v[204:207], v[216:219], v[80:83]
	v_mfma_f32_16x16x32_bf16 v[72:75], v[192:195], v[224:227], v[72:75]
	v_mfma_f32_16x16x32_bf16 v[64:67], v[204:207], v[224:227], v[64:67]
	v_mfma_f32_16x16x32_bf16 v[56:59], v[192:195], v[232:235], v[56:59]
	v_mfma_f32_16x16x32_bf16 v[48:51], v[204:207], v[232:235], v[48:51]
	v_mfma_f32_16x16x32_bf16 v[40:43], v[192:195], v[240:243], v[40:43]
	v_mfma_f32_16x16x32_bf16 v[36:39], v[204:207], v[240:243], v[36:39]
	v_mfma_f32_16x16x32_bf16 v[88:91], v[196:199], v[220:223], v[88:91]
	v_mfma_f32_16x16x32_bf16 v[80:83], v[210:213], v[220:223], v[80:83]
	v_mfma_f32_16x16x32_bf16 v[72:75], v[196:199], v[228:231], v[72:75]
	v_mfma_f32_16x16x32_bf16 v[64:67], v[210:213], v[228:231], v[64:67]
	v_mfma_f32_16x16x32_bf16 v[56:59], v[196:199], v[236:239], v[56:59]
	v_mfma_f32_16x16x32_bf16 v[48:51], v[210:213], v[236:239], v[48:51]
	v_mfma_f32_16x16x32_bf16 v[40:43], v[196:199], v[244:247], v[40:43]
	v_mfma_f32_16x16x32_bf16 v[36:39], v[210:213], v[244:247], v[36:39]
	s_barrier
	s_nop 0
	s_add_i32 s61, 0, 0x18000
	s_add_i32 s62, 0, 0x1c000
	ds_read_b128 v[164:167], v2 offset:32768
	ds_read_b128 v[168:171], v2 offset:33792
	ds_read_b128 v[172:175], v2 offset:34816
	ds_read_b128 v[176:179], v2 offset:35840
	ds_read_b128 v[192:195], v2 offset:49152
	ds_read_b128 v[196:199], v2 offset:50176
	ds_read_b128 v[204:207], v2 offset:51200
	ds_read_b128 v[210:213], v2 offset:52224
	s_add_u32 s34, s54, 0x80000
	s_addc_u32 s35, s55, 0
	s_mov_b32 m0, s82
	ds_read_b128 v[216:219], v203 offset:32768
	ds_read_b128 v[220:223], v203 offset:33792
	ds_read_b128 v[224:227], v203 offset:34816
	ds_read_b128 v[228:231], v203 offset:35840
	ds_read_b128 v[232:235], v203 offset:36864
	ds_read_b128 v[236:239], v203 offset:37888
	ds_read_b128 v[240:243], v203 offset:38912
	ds_read_b128 v[244:247], v203 offset:39936
	global_load_lds_dwordx4 v182, s[34:35]
	s_mov_b32 m0, s90
	s_nop 0
	global_load_lds_dwordx4 v186, s[34:35]
	s_waitcnt vmcnt(8) lgkmcnt(0)
	s_barrier
	v_mfma_f32_16x16x32_bf16 v[160:163], v[164:167], v[216:219], v[160:163]
	v_mfma_f32_16x16x32_bf16 v[156:159], v[172:175], v[216:219], v[156:159]
	v_mfma_f32_16x16x32_bf16 v[144:147], v[164:167], v[224:227], v[144:147]
	v_mfma_f32_16x16x32_bf16 v[140:143], v[172:175], v[224:227], v[140:143]
	v_mfma_f32_16x16x32_bf16 v[128:131], v[164:167], v[232:235], v[128:131]
	v_mfma_f32_16x16x32_bf16 v[124:127], v[172:175], v[232:235], v[124:127]
	v_mfma_f32_16x16x32_bf16 v[112:115], v[164:167], v[240:243], v[112:115]
	v_mfma_f32_16x16x32_bf16 v[108:111], v[172:175], v[240:243], v[108:111]
	v_mfma_f32_16x16x32_bf16 v[160:163], v[168:171], v[220:223], v[160:163]
	v_mfma_f32_16x16x32_bf16 v[156:159], v[176:179], v[220:223], v[156:159]
	v_mfma_f32_16x16x32_bf16 v[144:147], v[168:171], v[228:231], v[144:147]
	v_mfma_f32_16x16x32_bf16 v[140:143], v[176:179], v[228:231], v[140:143]
	v_mfma_f32_16x16x32_bf16 v[128:131], v[168:171], v[236:239], v[128:131]
	v_mfma_f32_16x16x32_bf16 v[124:127], v[176:179], v[236:239], v[124:127]
	v_mfma_f32_16x16x32_bf16 v[112:115], v[168:171], v[244:247], v[112:115]
	v_mfma_f32_16x16x32_bf16 v[108:111], v[176:179], v[244:247], v[108:111]
	v_mfma_f32_16x16x32_bf16 v[152:155], v[192:195], v[216:219], v[152:155]
	v_mfma_f32_16x16x32_bf16 v[148:151], v[204:207], v[216:219], v[148:151]
	v_mfma_f32_16x16x32_bf16 v[136:139], v[192:195], v[224:227], v[136:139]
	v_mfma_f32_16x16x32_bf16 v[132:135], v[204:207], v[224:227], v[132:135]
	v_mfma_f32_16x16x32_bf16 v[120:123], v[192:195], v[232:235], v[120:123]
	v_mfma_f32_16x16x32_bf16 v[116:119], v[204:207], v[232:235], v[116:119]
	v_mfma_f32_16x16x32_bf16 v[104:107], v[192:195], v[240:243], v[104:107]
	v_mfma_f32_16x16x32_bf16 v[100:103], v[204:207], v[240:243], v[100:103]
	v_mfma_f32_16x16x32_bf16 v[152:155], v[196:199], v[220:223], v[152:155]
	v_mfma_f32_16x16x32_bf16 v[148:151], v[210:213], v[220:223], v[148:151]
	v_mfma_f32_16x16x32_bf16 v[136:139], v[196:199], v[228:231], v[136:139]
	v_mfma_f32_16x16x32_bf16 v[132:135], v[210:213], v[228:231], v[132:135]
	v_mfma_f32_16x16x32_bf16 v[120:123], v[196:199], v[236:239], v[120:123]
	v_mfma_f32_16x16x32_bf16 v[116:119], v[210:213], v[236:239], v[116:119]
	v_mfma_f32_16x16x32_bf16 v[104:107], v[196:199], v[244:247], v[104:107]
	v_mfma_f32_16x16x32_bf16 v[100:103], v[210:213], v[244:247], v[100:103]
	s_barrier
	s_nop 0
	s_add_u32 s34, s52, 0x8000
	s_addc_u32 s35, s53, 0
	s_add_i32 s54, s61, s0
	s_mov_b32 m0, s54
	s_nop 0
	ds_read_b128 v[216:219], v203 offset:49152
	ds_read_b128 v[220:223], v203 offset:50176
	ds_read_b128 v[224:227], v203 offset:51200
	ds_read_b128 v[228:231], v203 offset:52224
	ds_read_b128 v[232:235], v203 offset:53248
	ds_read_b128 v[236:239], v203 offset:54272
	ds_read_b128 v[240:243], v203 offset:55296
	ds_read_b128 v[244:247], v203 offset:56320
	global_load_lds_dwordx4 v180, s[34:35]
	s_add_i32 m0, s54, 0x2000
	v_lshl_add_u64 v[250:251], s[34:35], 0, v[184:185]
	s_add_u32 s34, s52, 0xc000
	s_addc_u32 s35, s53, 0
	s_add_i32 s52, s62, s0
	global_load_lds_dwordx4 v[250:251], off
	s_mov_b32 m0, s52
	s_nop 0
	v_lshl_add_u64 v[200:201], v[200:201], 0, s[92:93]
	global_load_lds_dwordx4 v180, s[34:35]
	s_add_i32 m0, s52, 0x2000
	s_nop 0
	s_nop 0
	global_load_lds_dwordx4 v184, s[34:35]
	s_mov_b32 m0, s91
	s_nop 0
	global_load_lds_dwordx4 v[200:201], off
	v_lshl_add_u64 v[200:201], v[248:249], 0, s[92:93]
	s_mov_b32 m0, s30
	s_nop 0
	global_load_lds_dwordx4 v[200:201], off
	s_waitcnt vmcnt(8) lgkmcnt(0)
	s_barrier
	v_mfma_f32_16x16x32_bf16 v[96:99], v[164:167], v[216:219], v[96:99]
	v_mfma_f32_16x16x32_bf16 v[92:95], v[172:175], v[216:219], v[92:95]
	v_mfma_f32_16x16x32_bf16 v[84:87], v[164:167], v[224:227], v[84:87]
	v_mfma_f32_16x16x32_bf16 v[76:79], v[172:175], v[224:227], v[76:79]
	v_mfma_f32_16x16x32_bf16 v[68:71], v[164:167], v[232:235], v[68:71]
	v_mfma_f32_16x16x32_bf16 v[60:63], v[172:175], v[232:235], v[60:63]
	v_mfma_f32_16x16x32_bf16 v[52:55], v[164:167], v[240:243], v[52:55]
	v_mfma_f32_16x16x32_bf16 v[44:47], v[172:175], v[240:243], v[44:47]
	v_mfma_f32_16x16x32_bf16 v[96:99], v[168:171], v[220:223], v[96:99]
	v_mfma_f32_16x16x32_bf16 v[92:95], v[176:179], v[220:223], v[92:95]
	v_mfma_f32_16x16x32_bf16 v[84:87], v[168:171], v[228:231], v[84:87]
	v_mfma_f32_16x16x32_bf16 v[76:79], v[176:179], v[228:231], v[76:79]
	v_mfma_f32_16x16x32_bf16 v[68:71], v[168:171], v[236:239], v[68:71]
	v_mfma_f32_16x16x32_bf16 v[60:63], v[176:179], v[236:239], v[60:63]
	v_mfma_f32_16x16x32_bf16 v[52:55], v[168:171], v[244:247], v[52:55]
	v_mfma_f32_16x16x32_bf16 v[44:47], v[176:179], v[244:247], v[44:47]
	v_mfma_f32_16x16x32_bf16 v[88:91], v[192:195], v[216:219], v[88:91]
	v_mfma_f32_16x16x32_bf16 v[80:83], v[204:207], v[216:219], v[80:83]
	v_mfma_f32_16x16x32_bf16 v[72:75], v[192:195], v[224:227], v[72:75]
	v_mfma_f32_16x16x32_bf16 v[64:67], v[204:207], v[224:227], v[64:67]
	v_mfma_f32_16x16x32_bf16 v[56:59], v[192:195], v[232:235], v[56:59]
	v_mfma_f32_16x16x32_bf16 v[48:51], v[204:207], v[232:235], v[48:51]
	v_mfma_f32_16x16x32_bf16 v[40:43], v[192:195], v[240:243], v[40:43]
	v_mfma_f32_16x16x32_bf16 v[36:39], v[204:207], v[240:243], v[36:39]
	v_mfma_f32_16x16x32_bf16 v[88:91], v[196:199], v[220:223], v[88:91]
	v_mfma_f32_16x16x32_bf16 v[80:83], v[210:213], v[220:223], v[80:83]
	v_mfma_f32_16x16x32_bf16 v[72:75], v[196:199], v[228:231], v[72:75]
	v_mfma_f32_16x16x32_bf16 v[64:67], v[210:213], v[228:231], v[64:67]
	v_mfma_f32_16x16x32_bf16 v[56:59], v[196:199], v[236:239], v[56:59]
	v_mfma_f32_16x16x32_bf16 v[48:51], v[210:213], v[236:239], v[48:51]
	v_mfma_f32_16x16x32_bf16 v[40:43], v[196:199], v[244:247], v[40:43]
	v_mfma_f32_16x16x32_bf16 v[36:39], v[210:213], v[244:247], v[36:39]
	s_barrier
	s_add_i32 s60, s60, 2
	s_add_u32 s21, s21, 0x10000
	s_addc_u32 s59, s59, 0
	s_nop 0
	s_add_u32 s50, s50, 0x100
	s_addc_u32 s51, s51, 0
	s_cmp_gt_u32 s60, 5
	s_cbranch_scc0 .LBB0_707
	s_nop 0
	s_nop 0
	s_nop 0
	s_nop 0
	s_and_b64 vcc, exec, s[46:47]
	s_cbranch_vccz .LBB0_710
	s_barrier

.LBB0_788:
	s_add_u32 s34, s48, 0xfff80080
	s_addc_u32 s35, s49, -1
	s_nop 0
	s_add_i32 s57, 0, 0x10000
	s_cmp_eq_u32 s56, 28
	s_cselect_b32 s55, s23, s35
	s_cselect_b32 s54, s22, s34
	s_cselect_b32 s53, s43, s51
	s_cselect_b32 s52, s42, s15
	s_nop 0
	s_add_i32 s69, 0, 0x14000
	ds_read_b128 v[136:139], v200 offset:0
	ds_read_b128 v[140:143], v200 offset:1024
	ds_read_b128 v[144:147], v200 offset:2048
	ds_read_b128 v[148:151], v200 offset:3072
	ds_read_b128 v[152:155], v200 offset:16384
	ds_read_b128 v[156:159], v200 offset:17408
	ds_read_b128 v[160:163], v200 offset:18432
	ds_read_b128 v[174:177], v200 offset:19456
	s_add_i32 m0, s29, 0xc000
	ds_read_b128 v[178:181], v199
	ds_read_b128 v[182:185], v199 offset:1024
	ds_read_b128 v[186:189], v199 offset:2048
	ds_read_b128 v[190:193], v199 offset:3072
	ds_read_b128 v[194:197], v199 offset:4096
	ds_read_b128 v[210:213], v199 offset:5120
	ds_read_b128 v[240:243], v199 offset:6144
	ds_read_b128 v[244:247], v199 offset:7168
	global_load_lds_dwordx4 v170, s[48:49]
	s_add_i32 m0, s29, 0xe000
	s_nop 0
	s_nop 0
	global_load_lds_dwordx4 v172, s[48:49]
	s_waitcnt vmcnt(8) lgkmcnt(0)
	s_barrier
	v_mfma_f32_16x16x32_bf16 v[132:135], v[136:139], v[178:181], v[132:135]
	v_mfma_f32_16x16x32_bf16 v[128:131], v[144:147], v[178:181], v[128:131]
	v_mfma_f32_16x16x32_bf16 v[124:127], v[136:139], v[186:189], v[124:127]
	v_mfma_f32_16x16x32_bf16 v[120:123], v[144:147], v[186:189], v[120:123]
	v_mfma_f32_16x16x32_bf16 v[116:119], v[136:139], v[194:197], v[116:119]
	v_mfma_f32_16x16x32_bf16 v[112:115], v[144:147], v[194:197], v[112:115]
	v_mfma_f32_16x16x32_bf16 v[108:111], v[136:139], v[240:243], v[108:111]
	v_mfma_f32_16x16x32_bf16 v[104:107], v[144:147], v[240:243], v[104:107]
	v_mfma_f32_16x16x32_bf16 v[132:135], v[140:143], v[182:185], v[132:135]
	v_mfma_f32_16x16x32_bf16 v[128:131], v[148:151], v[182:185], v[128:131]
	v_mfma_f32_16x16x32_bf16 v[124:127], v[140:143], v[190:193], v[124:127]
	v_mfma_f32_16x16x32_bf16 v[120:123], v[148:151], v[190:193], v[120:123]
	v_mfma_f32_16x16x32_bf16 v[116:119], v[140:143], v[210:213], v[116:119]
	v_mfma_f32_16x16x32_bf16 v[112:115], v[148:151], v[210:213], v[112:115]
	v_mfma_f32_16x16x32_bf16 v[108:111], v[140:143], v[244:247], v[108:111]
	v_mfma_f32_16x16x32_bf16 v[104:107], v[148:151], v[244:247], v[104:107]
	v_mfma_f32_16x16x32_bf16 v[100:103], v[152:155], v[178:181], v[100:103]
	v_mfma_f32_16x16x32_bf16 v[96:99], v[160:163], v[178:181], v[96:99]
	v_mfma_f32_16x16x32_bf16 v[92:95], v[152:155], v[186:189], v[92:95]
	v_mfma_f32_16x16x32_bf16 v[88:91], v[160:163], v[186:189], v[88:91]
	v_mfma_f32_16x16x32_bf16 v[84:87], v[152:155], v[194:197], v[84:87]
	v_mfma_f32_16x16x32_bf16 v[80:83], v[160:163], v[194:197], v[80:83]
	v_mfma_f32_16x16x32_bf16 v[72:75], v[152:155], v[240:243], v[72:75]
	v_mfma_f32_16x16x32_bf16 v[64:67], v[160:163], v[240:243], v[64:67]
	v_mfma_f32_16x16x32_bf16 v[100:103], v[156:159], v[182:185], v[100:103]
	v_mfma_f32_16x16x32_bf16 v[96:99], v[174:177], v[182:185], v[96:99]
	v_mfma_f32_16x16x32_bf16 v[92:95], v[156:159], v[190:193], v[92:95]
	v_mfma_f32_16x16x32_bf16 v[88:91], v[174:177], v[190:193], v[88:91]
	v_mfma_f32_16x16x32_bf16 v[84:87], v[156:159], v[210:213], v[84:87]
	v_mfma_f32_16x16x32_bf16 v[80:83], v[174:177], v[210:213], v[80:83]
	v_mfma_f32_16x16x32_bf16 v[72:75], v[156:159], v[244:247], v[72:75]
	v_mfma_f32_16x16x32_bf16 v[64:67], v[174:177], v[244:247], v[64:67]
	s_barrier
	s_add_i32 s34, s57, s0
	s_mov_b32 m0, s34
	s_nop 0
	ds_read_b128 v[178:181], v199 offset:16384
	ds_read_b128 v[182:185], v199 offset:17408
	ds_read_b128 v[186:189], v199 offset:18432
	ds_read_b128 v[190:193], v199 offset:19456
	ds_read_b128 v[194:197], v199 offset:20480
	ds_read_b128 v[210:213], v199 offset:21504
	ds_read_b128 v[240:243], v199 offset:22528
	ds_read_b128 v[244:247], v199 offset:23552
	global_load_lds_dwordx4 v32, s[52:53]
	s_add_i32 m0, s34, 0x2000
	s_add_u32 s34, s52, 0x4000
	s_addc_u32 s35, s53, 0
	s_add_i32 s57, s69, s0
	global_load_lds_dwordx4 v166, s[52:53]
	s_mov_b32 m0, s57
	s_nop 0
	v_lshl_add_u64 v[248:249], s[54:55], 0, v[164:165]
	global_load_lds_dwordx4 v32, s[34:35]
	s_add_i32 m0, s57, 0x2000
	v_lshl_add_u64 v[250:251], s[54:55], 0, v[168:169]
	global_load_lds_dwordx4 v166, s[34:35]
	s_mov_b32 m0, s29
	s_nop 0
	global_load_lds_dwordx4 v164, s[54:55]
	s_mov_b32 m0, s45
	s_nop 0
	global_load_lds_dwordx4 v168, s[54:55]
	s_waitcnt vmcnt(8) lgkmcnt(0)
	s_barrier
	v_mfma_f32_16x16x32_bf16 v[76:79], v[136:139], v[178:181], v[76:79]
	v_mfma_f32_16x16x32_bf16 v[68:71], v[144:147], v[178:181], v[68:71]
	v_mfma_f32_16x16x32_bf16 v[60:63], v[136:139], v[186:189], v[60:63]
	v_mfma_f32_16x16x32_bf16 v[56:59], v[144:147], v[186:189], v[56:59]
	v_mfma_f32_16x16x32_bf16 v[52:55], v[136:139], v[194:197], v[52:55]
	v_mfma_f32_16x16x32_bf16 v[48:51], v[144:147], v[194:197], v[48:51]
	v_mfma_f32_16x16x32_bf16 v[44:47], v[136:139], v[240:243], v[44:47]
	v_mfma_f32_16x16x32_bf16 v[40:43], v[144:147], v[240:243], v[40:43]
	v_mfma_f32_16x16x32_bf16 v[76:79], v[140:143], v[182:185], v[76:79]
	v_mfma_f32_16x16x32_bf16 v[68:71], v[148:151], v[182:185], v[68:71]
	v_mfma_f32_16x16x32_bf16 v[60:63], v[140:143], v[190:193], v[60:63]
	v_mfma_f32_16x16x32_bf16 v[56:59], v[148:151], v[190:193], v[56:59]
	v_mfma_f32_16x16x32_bf16 v[52:55], v[140:143], v[210:213], v[52:55]
	v_mfma_f32_16x16x32_bf16 v[48:51], v[148:151], v[210:213], v[48:51]
	v_mfma_f32_16x16x32_bf16 v[44:47], v[140:143], v[244:247], v[44:47]
	v_mfma_f32_16x16x32_bf16 v[40:43], v[148:151], v[244:247], v[40:43]
	v_mfma_f32_16x16x32_bf16 v[36:39], v[152:155], v[178:181], v[36:39]
	v_mfma_f32_16x16x32_bf16 v[28:31], v[160:163], v[178:181], v[28:31]
	v_mfma_f32_16x16x32_bf16 v[24:27], v[152:155], v[186:189], v[24:27]
	v_mfma_f32_16x16x32_bf16 v[20:23], v[160:163], v[186:189], v[20:23]
	v_mfma_f32_16x16x32_bf16 v[16:19], v[152:155], v[194:197], v[16:19]
	v_mfma_f32_16x16x32_bf16 v[12:15], v[160:163], v[194:197], v[12:15]
	v_mfma_f32_16x16x32_bf16 v[8:11], v[152:155], v[240:243], v[8:11]
	v_mfma_f32_16x16x32_bf16 v[2:5], v[160:163], v[240:243], v[4:7]
	v_mfma_f32_16x16x32_bf16 v[36:39], v[156:159], v[182:185], v[36:39]
	v_mfma_f32_16x16x32_bf16 v[28:31], v[174:177], v[182:185], v[28:31]
	v_mfma_f32_16x16x32_bf16 v[24:27], v[156:159], v[190:193], v[24:27]
	v_mfma_f32_16x16x32_bf16 v[20:23], v[174:177], v[190:193], v[20:23]
	v_mfma_f32_16x16x32_bf16 v[16:19], v[156:159], v[210:213], v[16:19]
	v_mfma_f32_16x16x32_bf16 v[12:15], v[174:177], v[210:213], v[12:15]
	v_mfma_f32_16x16x32_bf16 v[8:11], v[156:159], v[244:247], v[8:11]
	v_mfma_f32_16x16x32_bf16 v[2:5], v[174:177], v[244:247], v[2:5]
	s_barrier
	s_nop 0
	s_add_i32 s57, 0, 0x18000
	s_add_i32 s69, 0, 0x1c000
	ds_read_b128 v[136:139], v200 offset:32768
	ds_read_b128 v[140:143], v200 offset:33792
	ds_read_b128 v[144:147], v200 offset:34816
	ds_read_b128 v[148:151], v200 offset:35840
	ds_read_b128 v[152:155], v200 offset:49152
	ds_read_b128 v[156:159], v200 offset:50176
	ds_read_b128 v[160:163], v200 offset:51200
	ds_read_b128 v[174:177], v200 offset:52224
	s_add_u32 s34, s54, 0x80000
	s_addc_u32 s35, s55, 0
	s_mov_b32 m0, s82
	ds_read_b128 v[178:181], v199 offset:32768
	ds_read_b128 v[182:185], v199 offset:33792
	ds_read_b128 v[186:189], v199 offset:34816
	ds_read_b128 v[190:193], v199 offset:35840
	ds_read_b128 v[194:197], v199 offset:36864
	ds_read_b128 v[210:213], v199 offset:37888
	ds_read_b128 v[240:243], v199 offset:38912
	ds_read_b128 v[244:247], v199 offset:39936
	global_load_lds_dwordx4 v164, s[34:35]
	s_mov_b32 m0, s90
	s_nop 0
	global_load_lds_dwordx4 v168, s[34:35]
	s_waitcnt vmcnt(8) lgkmcnt(0)
	s_barrier
	v_mfma_f32_16x16x32_bf16 v[132:135], v[136:139], v[178:181], v[132:135]
	v_mfma_f32_16x16x32_bf16 v[128:131], v[144:147], v[178:181], v[128:131]
	v_mfma_f32_16x16x32_bf16 v[124:127], v[136:139], v[186:189], v[124:127]
	v_mfma_f32_16x16x32_bf16 v[120:123], v[144:147], v[186:189], v[120:123]
	v_mfma_f32_16x16x32_bf16 v[116:119], v[136:139], v[194:197], v[116:119]
	v_mfma_f32_16x16x32_bf16 v[112:115], v[144:147], v[194:197], v[112:115]
	v_mfma_f32_16x16x32_bf16 v[108:111], v[136:139], v[240:243], v[108:111]
	v_mfma_f32_16x16x32_bf16 v[104:107], v[144:147], v[240:243], v[104:107]
	v_mfma_f32_16x16x32_bf16 v[132:135], v[140:143], v[182:185], v[132:135]
	v_mfma_f32_16x16x32_bf16 v[128:131], v[148:151], v[182:185], v[128:131]
	v_mfma_f32_16x16x32_bf16 v[124:127], v[140:143], v[190:193], v[124:127]
	v_mfma_f32_16x16x32_bf16 v[120:123], v[148:151], v[190:193], v[120:123]
	v_mfma_f32_16x16x32_bf16 v[116:119], v[140:143], v[210:213], v[116:119]
	v_mfma_f32_16x16x32_bf16 v[112:115], v[148:151], v[210:213], v[112:115]
	v_mfma_f32_16x16x32_bf16 v[108:111], v[140:143], v[244:247], v[108:111]
	v_mfma_f32_16x16x32_bf16 v[104:107], v[148:151], v[244:247], v[104:107]
	v_mfma_f32_16x16x32_bf16 v[100:103], v[152:155], v[178:181], v[100:103]
	v_mfma_f32_16x16x32_bf16 v[96:99], v[160:163], v[178:181], v[96:99]
	v_mfma_f32_16x16x32_bf16 v[92:95], v[152:155], v[186:189], v[92:95]
	v_mfma_f32_16x16x32_bf16 v[88:91], v[160:163], v[186:189], v[88:91]
	v_mfma_f32_16x16x32_bf16 v[84:87], v[152:155], v[194:197], v[84:87]
	v_mfma_f32_16x16x32_bf16 v[80:83], v[160:163], v[194:197], v[80:83]
	v_mfma_f32_16x16x32_bf16 v[72:75], v[152:155], v[240:243], v[72:75]
	v_mfma_f32_16x16x32_bf16 v[64:67], v[160:163], v[240:243], v[64:67]
	v_mfma_f32_16x16x32_bf16 v[100:103], v[156:159], v[182:185], v[100:103]
	v_mfma_f32_16x16x32_bf16 v[96:99], v[174:177], v[182:185], v[96:99]
	v_mfma_f32_16x16x32_bf16 v[92:95], v[156:159], v[190:193], v[92:95]
	v_mfma_f32_16x16x32_bf16 v[88:91], v[174:177], v[190:193], v[88:91]
	v_mfma_f32_16x16x32_bf16 v[84:87], v[156:159], v[210:213], v[84:87]
	v_mfma_f32_16x16x32_bf16 v[80:83], v[174:177], v[210:213], v[80:83]
	v_mfma_f32_16x16x32_bf16 v[72:75], v[156:159], v[244:247], v[72:75]
	v_mfma_f32_16x16x32_bf16 v[64:67], v[174:177], v[244:247], v[64:67]
	s_barrier
	s_nop 0
	s_add_u32 s34, s52, 0x8000
	s_addc_u32 s35, s53, 0
	s_add_i32 s54, s57, s0
	s_mov_b32 m0, s54
	s_nop 0
	ds_read_b128 v[178:181], v199 offset:49152
	ds_read_b128 v[182:185], v199 offset:50176
	ds_read_b128 v[186:189], v199 offset:51200
	ds_read_b128 v[190:193], v199 offset:52224
	ds_read_b128 v[194:197], v199 offset:53248
	ds_read_b128 v[210:213], v199 offset:54272
	ds_read_b128 v[240:243], v199 offset:55296
	ds_read_b128 v[244:247], v199 offset:56320
	global_load_lds_dwordx4 v32, s[34:35]
	s_add_i32 m0, s54, 0x2000
	v_lshl_add_u64 v[6:7], s[34:35], 0, v[166:167]
	s_add_u32 s34, s52, 0xc000
	s_addc_u32 s35, s53, 0
	s_add_i32 s52, s69, s0
	global_load_lds_dwordx4 v[6:7], off
	s_mov_b32 m0, s52
	s_nop 0
	global_load_lds_dwordx4 v32, s[34:35]
	s_add_i32 m0, s52, 0x2000
	s_nop 0
	s_nop 0
	global_load_lds_dwordx4 v166, s[34:35]
	v_lshl_add_u64 v[6:7], v[248:249], 0, s[92:93]
	s_mov_b32 m0, s91
	s_nop 0
	global_load_lds_dwordx4 v[6:7], off
	v_lshl_add_u64 v[6:7], v[250:251], 0, s[92:93]
	s_mov_b32 m0, s30
	s_nop 0
	global_load_lds_dwordx4 v[6:7], off
	s_waitcnt vmcnt(8) lgkmcnt(0)
	s_barrier
	v_mfma_f32_16x16x32_bf16 v[76:79], v[136:139], v[178:181], v[76:79]
	v_mfma_f32_16x16x32_bf16 v[68:71], v[144:147], v[178:181], v[68:71]
	v_mfma_f32_16x16x32_bf16 v[60:63], v[136:139], v[186:189], v[60:63]
	v_mfma_f32_16x16x32_bf16 v[56:59], v[144:147], v[186:189], v[56:59]
	v_mfma_f32_16x16x32_bf16 v[52:55], v[136:139], v[194:197], v[52:55]
	v_mfma_f32_16x16x32_bf16 v[48:51], v[144:147], v[194:197], v[48:51]
	v_mfma_f32_16x16x32_bf16 v[44:47], v[136:139], v[240:243], v[44:47]
	v_mfma_f32_16x16x32_bf16 v[40:43], v[144:147], v[240:243], v[40:43]
	v_mfma_f32_16x16x32_bf16 v[76:79], v[140:143], v[182:185], v[76:79]
	v_mfma_f32_16x16x32_bf16 v[68:71], v[148:151], v[182:185], v[68:71]
	v_mfma_f32_16x16x32_bf16 v[60:63], v[140:143], v[190:193], v[60:63]
	v_mfma_f32_16x16x32_bf16 v[56:59], v[148:151], v[190:193], v[56:59]
	v_mfma_f32_16x16x32_bf16 v[52:55], v[140:143], v[210:213], v[52:55]
	v_mfma_f32_16x16x32_bf16 v[48:51], v[148:151], v[210:213], v[48:51]
	v_mfma_f32_16x16x32_bf16 v[44:47], v[140:143], v[244:247], v[44:47]
	v_mfma_f32_16x16x32_bf16 v[40:43], v[148:151], v[244:247], v[40:43]
	v_mfma_f32_16x16x32_bf16 v[36:39], v[152:155], v[178:181], v[36:39]
	v_mfma_f32_16x16x32_bf16 v[28:31], v[160:163], v[178:181], v[28:31]
	v_mfma_f32_16x16x32_bf16 v[24:27], v[152:155], v[186:189], v[24:27]
	v_mfma_f32_16x16x32_bf16 v[20:23], v[160:163], v[186:189], v[20:23]
	v_mfma_f32_16x16x32_bf16 v[16:19], v[152:155], v[194:197], v[16:19]
	v_mfma_f32_16x16x32_bf16 v[12:15], v[160:163], v[194:197], v[12:15]
	v_mfma_f32_16x16x32_bf16 v[6:9], v[152:155], v[240:243], v[8:11]
	v_mfma_f32_16x16x32_bf16 v[2:5], v[160:163], v[240:243], v[2:5]
	v_mfma_f32_16x16x32_bf16 v[36:39], v[156:159], v[182:185], v[36:39]
	v_mfma_f32_16x16x32_bf16 v[28:31], v[174:177], v[182:185], v[28:31]
	v_mfma_f32_16x16x32_bf16 v[24:27], v[156:159], v[190:193], v[24:27]
	v_mfma_f32_16x16x32_bf16 v[20:23], v[174:177], v[190:193], v[20:23]
	v_mfma_f32_16x16x32_bf16 v[16:19], v[156:159], v[210:213], v[16:19]
	v_mfma_f32_16x16x32_bf16 v[12:15], v[174:177], v[210:213], v[12:15]
	v_mfma_f32_16x16x32_bf16 v[8:11], v[156:159], v[244:247], v[6:9]
	v_mfma_f32_16x16x32_bf16 v[4:7], v[174:177], v[244:247], v[2:5]
	s_barrier
	s_add_i32 s56, s56, 2
	s_add_u32 s15, s15, 0x10000
	s_addc_u32 s51, s51, 0
	s_nop 0
	s_add_u32 s48, s48, 0x100
	s_addc_u32 s49, s49, 0
	s_cmp_gt_u32 s56, 29
	s_cbranch_scc0 .LBB0_788
	s_nop 0
	s_nop 0
	s_nop 0
	s_nop 0
	s_nop 0
	s_nop 0
	s_and_b64 vcc, exec, s[46:47]
	s_cbranch_vccz .LBB0_791
	s_barrier

.LBB0_877:
	s_add_u32 s62, s60, 0x100
	s_addc_u32 s63, s61, 0
	s_nop 0
	s_add_i32 s34, 0, 0x10000
	s_cmp_eq_u32 s49, 60
	s_cselect_b32 s67, s51, s63
	s_cselect_b32 s66, s50, s62
	s_cselect_b32 s65, s53, s28
	s_cselect_b32 s64, s52, s13
	s_nop 0
	s_add_i32 s55, 0, 0x14000
	ds_read_b128 v[132:135], v190 offset:0
	ds_read_b128 v[136:139], v190 offset:1024
	ds_read_b128 v[140:143], v190 offset:2048
	ds_read_b128 v[144:147], v190 offset:3072
	ds_read_b128 v[148:151], v190 offset:16384
	ds_read_b128 v[152:155], v190 offset:17408
	ds_read_b128 v[168:171], v190 offset:18432
	ds_read_b128 v[172:175], v190 offset:19456
	s_add_i32 m0, s29, 0xc000
	ds_read_b128 v[176:179], v189
	ds_read_b128 v[180:183], v189 offset:1024
	ds_read_b128 v[184:187], v189 offset:2048
	ds_read_b128 v[192:195], v189 offset:3072
	ds_read_b128 v[210:213], v189 offset:4096
	ds_read_b128 v[234:237], v189 offset:5120
	ds_read_b128 v[238:241], v189 offset:6144
	ds_read_b128 v[242:245], v189 offset:7168
	global_load_lds_dwordx4 v164, s[60:61]
	s_add_i32 m0, s29, 0xe000
	s_nop 0
	s_nop 0
	global_load_lds_dwordx4 v166, s[60:61]
	s_waitcnt vmcnt(8) lgkmcnt(0)
	s_barrier
	v_mfma_f32_16x16x32_bf16 v[128:131], v[132:135], v[176:179], v[128:131]
	v_mfma_f32_16x16x32_bf16 v[124:127], v[140:143], v[176:179], v[124:127]
	v_mfma_f32_16x16x32_bf16 v[112:115], v[132:135], v[184:187], v[112:115]
	v_mfma_f32_16x16x32_bf16 v[108:111], v[140:143], v[184:187], v[108:111]
	v_mfma_f32_16x16x32_bf16 v[96:99], v[132:135], v[210:213], v[96:99]
	v_mfma_f32_16x16x32_bf16 v[92:95], v[140:143], v[210:213], v[92:95]
	v_mfma_f32_16x16x32_bf16 v[80:83], v[132:135], v[238:241], v[80:83]
	v_mfma_f32_16x16x32_bf16 v[76:79], v[140:143], v[238:241], v[76:79]
	v_mfma_f32_16x16x32_bf16 v[128:131], v[136:139], v[180:183], v[128:131]
	v_mfma_f32_16x16x32_bf16 v[124:127], v[144:147], v[180:183], v[124:127]
	v_mfma_f32_16x16x32_bf16 v[112:115], v[136:139], v[192:195], v[112:115]
	v_mfma_f32_16x16x32_bf16 v[108:111], v[144:147], v[192:195], v[108:111]
	v_mfma_f32_16x16x32_bf16 v[96:99], v[136:139], v[234:237], v[96:99]
	v_mfma_f32_16x16x32_bf16 v[92:95], v[144:147], v[234:237], v[92:95]
	v_mfma_f32_16x16x32_bf16 v[80:83], v[136:139], v[242:245], v[80:83]
	v_mfma_f32_16x16x32_bf16 v[76:79], v[144:147], v[242:245], v[76:79]
	v_mfma_f32_16x16x32_bf16 v[120:123], v[148:151], v[176:179], v[120:123]
	v_mfma_f32_16x16x32_bf16 v[116:119], v[168:171], v[176:179], v[116:119]
	v_mfma_f32_16x16x32_bf16 v[104:107], v[148:151], v[184:187], v[104:107]
	v_mfma_f32_16x16x32_bf16 v[100:103], v[168:171], v[184:187], v[100:103]
	v_mfma_f32_16x16x32_bf16 v[88:91], v[148:151], v[210:213], v[88:91]
	v_mfma_f32_16x16x32_bf16 v[84:87], v[168:171], v[210:213], v[84:87]
	v_mfma_f32_16x16x32_bf16 v[72:75], v[148:151], v[238:241], v[72:75]
	v_mfma_f32_16x16x32_bf16 v[68:71], v[168:171], v[238:241], v[68:71]
	v_mfma_f32_16x16x32_bf16 v[120:123], v[152:155], v[180:183], v[120:123]
	v_mfma_f32_16x16x32_bf16 v[116:119], v[172:175], v[180:183], v[116:119]
	v_mfma_f32_16x16x32_bf16 v[104:107], v[152:155], v[192:195], v[104:107]
	v_mfma_f32_16x16x32_bf16 v[100:103], v[172:175], v[192:195], v[100:103]
	v_mfma_f32_16x16x32_bf16 v[88:91], v[152:155], v[234:237], v[88:91]
	v_mfma_f32_16x16x32_bf16 v[84:87], v[172:175], v[234:237], v[84:87]
	v_mfma_f32_16x16x32_bf16 v[72:75], v[152:155], v[242:245], v[72:75]
	v_mfma_f32_16x16x32_bf16 v[68:71], v[172:175], v[242:245], v[68:71]
	s_barrier
	s_add_i32 s34, s34, s0
	s_mov_b32 m0, s34
	s_nop 0
	ds_read_b128 v[176:179], v189 offset:16384
	ds_read_b128 v[180:183], v189 offset:17408
	ds_read_b128 v[184:187], v189 offset:18432
	ds_read_b128 v[192:195], v189 offset:19456
	ds_read_b128 v[210:213], v189 offset:20480
	ds_read_b128 v[234:237], v189 offset:21504
	ds_read_b128 v[238:241], v189 offset:22528
	ds_read_b128 v[242:245], v189 offset:23552
	global_load_lds_dwordx4 v156, s[64:65]
	s_add_i32 m0, s34, 0x2000
	s_add_u32 s34, s64, 0x4000
	s_addc_u32 s35, s65, 0
	s_add_i32 s55, s55, s0
	global_load_lds_dwordx4 v160, s[64:65]
	s_mov_b32 m0, s55
	s_nop 0
	global_load_lds_dwordx4 v156, s[34:35]
	s_add_i32 m0, s55, 0x2000
	s_nop 0
	s_nop 0
	global_load_lds_dwordx4 v160, s[34:35]
	s_mov_b32 m0, s29
	s_nop 0
	global_load_lds_dwordx4 v158, s[66:67]
	s_mov_b32 m0, s45
	s_nop 0
	global_load_lds_dwordx4 v162, s[66:67]
	s_waitcnt vmcnt(8) lgkmcnt(0)
	s_barrier
	v_mfma_f32_16x16x32_bf16 v[64:67], v[132:135], v[176:179], v[64:67]
	v_mfma_f32_16x16x32_bf16 v[60:63], v[140:143], v[176:179], v[60:63]
	v_mfma_f32_16x16x32_bf16 v[48:51], v[132:135], v[184:187], v[48:51]
	v_mfma_f32_16x16x32_bf16 v[44:47], v[140:143], v[184:187], v[44:47]
	v_mfma_f32_16x16x32_bf16 v[30:33], v[132:135], v[210:213], v[30:33]
	v_mfma_f32_16x16x32_bf16 v[26:29], v[140:143], v[210:213], v[26:29]
	v_mfma_f32_16x16x32_bf16 v[14:17], v[132:135], v[238:241], v[14:17]
	v_mfma_f32_16x16x32_bf16 v[10:13], v[140:143], v[238:241], v[10:13]
	v_mfma_f32_16x16x32_bf16 v[64:67], v[136:139], v[180:183], v[64:67]
	v_mfma_f32_16x16x32_bf16 v[60:63], v[144:147], v[180:183], v[60:63]
	v_mfma_f32_16x16x32_bf16 v[48:51], v[136:139], v[192:195], v[48:51]
	v_mfma_f32_16x16x32_bf16 v[44:47], v[144:147], v[192:195], v[44:47]
	v_mfma_f32_16x16x32_bf16 v[30:33], v[136:139], v[234:237], v[30:33]
	v_mfma_f32_16x16x32_bf16 v[26:29], v[144:147], v[234:237], v[26:29]
	v_mfma_f32_16x16x32_bf16 v[14:17], v[136:139], v[242:245], v[14:17]
	v_mfma_f32_16x16x32_bf16 v[10:13], v[144:147], v[242:245], v[10:13]
	v_mfma_f32_16x16x32_bf16 v[56:59], v[148:151], v[176:179], v[56:59]
	v_mfma_f32_16x16x32_bf16 v[52:55], v[168:171], v[176:179], v[52:55]
	v_mfma_f32_16x16x32_bf16 v[40:43], v[148:151], v[184:187], v[40:43]
	v_mfma_f32_16x16x32_bf16 v[36:39], v[168:171], v[184:187], v[36:39]
	v_mfma_f32_16x16x32_bf16 v[22:25], v[148:151], v[210:213], v[22:25]
	v_mfma_f32_16x16x32_bf16 v[18:21], v[168:171], v[210:213], v[18:21]
	v_mfma_f32_16x16x32_bf16 v[6:9], v[148:151], v[238:241], v[6:9]
	v_mfma_f32_16x16x32_bf16 v[2:5], v[168:171], v[238:241], v[2:5]
	v_mfma_f32_16x16x32_bf16 v[56:59], v[152:155], v[180:183], v[56:59]
	v_mfma_f32_16x16x32_bf16 v[52:55], v[172:175], v[180:183], v[52:55]
	v_mfma_f32_16x16x32_bf16 v[40:43], v[152:155], v[192:195], v[40:43]
	v_mfma_f32_16x16x32_bf16 v[36:39], v[172:175], v[192:195], v[36:39]
	v_mfma_f32_16x16x32_bf16 v[22:25], v[152:155], v[234:237], v[22:25]
	v_mfma_f32_16x16x32_bf16 v[18:21], v[172:175], v[234:237], v[18:21]
	v_mfma_f32_16x16x32_bf16 v[6:9], v[152:155], v[242:245], v[6:9]
	v_mfma_f32_16x16x32_bf16 v[2:5], v[172:175], v[242:245], v[2:5]
	s_barrier
	s_nop 0
	s_add_i32 s55, 0, 0x18000
	s_add_i32 s58, 0, 0x1c000
	ds_read_b128 v[132:135], v190 offset:32768
	ds_read_b128 v[136:139], v190 offset:33792
	ds_read_b128 v[140:143], v190 offset:34816
	ds_read_b128 v[144:147], v190 offset:35840
	ds_read_b128 v[148:151], v190 offset:49152
	ds_read_b128 v[152:155], v190 offset:50176
	ds_read_b128 v[168:171], v190 offset:51200
	ds_read_b128 v[172:175], v190 offset:52224
	s_add_u32 s34, s66, 0x100000
	s_addc_u32 s35, s67, 0
	s_mov_b32 m0, s82
	ds_read_b128 v[176:179], v189 offset:32768
	ds_read_b128 v[180:183], v189 offset:33792
	ds_read_b128 v[184:187], v189 offset:34816
	ds_read_b128 v[192:195], v189 offset:35840
	ds_read_b128 v[210:213], v189 offset:36864
	ds_read_b128 v[234:237], v189 offset:37888
	ds_read_b128 v[238:241], v189 offset:38912
	ds_read_b128 v[242:245], v189 offset:39936
	global_load_lds_dwordx4 v158, s[34:35]
	s_mov_b32 m0, s90
	s_nop 0
	global_load_lds_dwordx4 v162, s[34:35]
	s_waitcnt vmcnt(8) lgkmcnt(0)
	s_barrier
	v_mfma_f32_16x16x32_bf16 v[128:131], v[132:135], v[176:179], v[128:131]
	v_mfma_f32_16x16x32_bf16 v[124:127], v[140:143], v[176:179], v[124:127]
	v_mfma_f32_16x16x32_bf16 v[112:115], v[132:135], v[184:187], v[112:115]
	v_mfma_f32_16x16x32_bf16 v[108:111], v[140:143], v[184:187], v[108:111]
	v_mfma_f32_16x16x32_bf16 v[96:99], v[132:135], v[210:213], v[96:99]
	v_mfma_f32_16x16x32_bf16 v[92:95], v[140:143], v[210:213], v[92:95]
	v_mfma_f32_16x16x32_bf16 v[80:83], v[132:135], v[238:241], v[80:83]
	v_mfma_f32_16x16x32_bf16 v[76:79], v[140:143], v[238:241], v[76:79]
	v_mfma_f32_16x16x32_bf16 v[128:131], v[136:139], v[180:183], v[128:131]
	v_mfma_f32_16x16x32_bf16 v[124:127], v[144:147], v[180:183], v[124:127]
	v_mfma_f32_16x16x32_bf16 v[112:115], v[136:139], v[192:195], v[112:115]
	v_mfma_f32_16x16x32_bf16 v[108:111], v[144:147], v[192:195], v[108:111]
	v_mfma_f32_16x16x32_bf16 v[96:99], v[136:139], v[234:237], v[96:99]
	v_mfma_f32_16x16x32_bf16 v[92:95], v[144:147], v[234:237], v[92:95]
	v_mfma_f32_16x16x32_bf16 v[80:83], v[136:139], v[242:245], v[80:83]
	v_mfma_f32_16x16x32_bf16 v[76:79], v[144:147], v[242:245], v[76:79]
	v_mfma_f32_16x16x32_bf16 v[120:123], v[148:151], v[176:179], v[120:123]
	v_mfma_f32_16x16x32_bf16 v[116:119], v[168:171], v[176:179], v[116:119]
	v_mfma_f32_16x16x32_bf16 v[104:107], v[148:151], v[184:187], v[104:107]
	v_mfma_f32_16x16x32_bf16 v[100:103], v[168:171], v[184:187], v[100:103]
	v_mfma_f32_16x16x32_bf16 v[88:91], v[148:151], v[210:213], v[88:91]
	v_mfma_f32_16x16x32_bf16 v[84:87], v[168:171], v[210:213], v[84:87]
	v_mfma_f32_16x16x32_bf16 v[72:75], v[148:151], v[238:241], v[72:75]
	v_mfma_f32_16x16x32_bf16 v[68:71], v[168:171], v[238:241], v[68:71]
	v_mfma_f32_16x16x32_bf16 v[120:123], v[152:155], v[180:183], v[120:123]
	v_mfma_f32_16x16x32_bf16 v[116:119], v[172:175], v[180:183], v[116:119]
	v_mfma_f32_16x16x32_bf16 v[104:107], v[152:155], v[192:195], v[104:107]
	v_mfma_f32_16x16x32_bf16 v[100:103], v[172:175], v[192:195], v[100:103]
	v_mfma_f32_16x16x32_bf16 v[88:91], v[152:155], v[234:237], v[88:91]
	v_mfma_f32_16x16x32_bf16 v[84:87], v[172:175], v[234:237], v[84:87]
	v_mfma_f32_16x16x32_bf16 v[72:75], v[152:155], v[242:245], v[72:75]
	v_mfma_f32_16x16x32_bf16 v[68:71], v[172:175], v[242:245], v[68:71]
	s_barrier
	s_nop 0
	s_add_u32 s34, s64, 0x8000
	s_addc_u32 s35, s65, 0
	s_add_i32 s55, s55, s0
	s_mov_b32 m0, s55
	s_nop 0
	ds_read_b128 v[176:179], v189 offset:49152
	ds_read_b128 v[180:183], v189 offset:50176
	ds_read_b128 v[184:187], v189 offset:51200
	ds_read_b128 v[192:195], v189 offset:52224
	ds_read_b128 v[210:213], v189 offset:53248
	ds_read_b128 v[234:237], v189 offset:54272
	ds_read_b128 v[238:241], v189 offset:55296
	ds_read_b128 v[242:245], v189 offset:56320
	global_load_lds_dwordx4 v156, s[34:35]
	s_add_i32 m0, s55, 0x2000
	s_mov_b64 s[100:101], s[34:35]
	s_nop 0
	s_add_u32 s34, s64, 0xc000
	s_addc_u32 s35, s65, 0
	s_add_i32 s55, s58, s0
	global_load_lds_dwordx4 v160, s[100:101]
	s_mov_b32 m0, s55
	s_nop 0
	global_load_lds_dwordx4 v156, s[34:35]
	s_add_i32 m0, s55, 0x2000
	s_nop 0
	s_nop 0
	global_load_lds_dwordx4 v160, s[34:35]
	s_mov_b32 m0, s91
	s_nop 0
	s_add_u32 s100, s66, s92
	s_addc_u32 s101, s67, s93
	global_load_lds_dwordx4 v158, s[100:101]
	s_mov_b32 m0, s30
	s_nop 0
	s_add_u32 s100, s66, s92
	s_addc_u32 s101, s67, s93
	global_load_lds_dwordx4 v162, s[100:101]
	s_waitcnt vmcnt(8) lgkmcnt(0)
	s_barrier
	v_mfma_f32_16x16x32_bf16 v[64:67], v[132:135], v[176:179], v[64:67]
	v_mfma_f32_16x16x32_bf16 v[60:63], v[140:143], v[176:179], v[60:63]
	v_mfma_f32_16x16x32_bf16 v[48:51], v[132:135], v[184:187], v[48:51]
	v_mfma_f32_16x16x32_bf16 v[44:47], v[140:143], v[184:187], v[44:47]
	v_mfma_f32_16x16x32_bf16 v[30:33], v[132:135], v[210:213], v[30:33]
	v_mfma_f32_16x16x32_bf16 v[26:29], v[140:143], v[210:213], v[26:29]
	v_mfma_f32_16x16x32_bf16 v[14:17], v[132:135], v[238:241], v[14:17]
	v_mfma_f32_16x16x32_bf16 v[10:13], v[140:143], v[238:241], v[10:13]
	v_mfma_f32_16x16x32_bf16 v[64:67], v[136:139], v[180:183], v[64:67]
	v_mfma_f32_16x16x32_bf16 v[60:63], v[144:147], v[180:183], v[60:63]
	v_mfma_f32_16x16x32_bf16 v[48:51], v[136:139], v[192:195], v[48:51]
	v_mfma_f32_16x16x32_bf16 v[44:47], v[144:147], v[192:195], v[44:47]
	v_mfma_f32_16x16x32_bf16 v[30:33], v[136:139], v[234:237], v[30:33]
	v_mfma_f32_16x16x32_bf16 v[26:29], v[144:147], v[234:237], v[26:29]
	v_mfma_f32_16x16x32_bf16 v[14:17], v[136:139], v[242:245], v[14:17]
	v_mfma_f32_16x16x32_bf16 v[10:13], v[144:147], v[242:245], v[10:13]
	v_mfma_f32_16x16x32_bf16 v[56:59], v[148:151], v[176:179], v[56:59]
	v_mfma_f32_16x16x32_bf16 v[52:55], v[168:171], v[176:179], v[52:55]
	v_mfma_f32_16x16x32_bf16 v[40:43], v[148:151], v[184:187], v[40:43]
	v_mfma_f32_16x16x32_bf16 v[36:39], v[168:171], v[184:187], v[36:39]
	v_mfma_f32_16x16x32_bf16 v[22:25], v[148:151], v[210:213], v[22:25]
	v_mfma_f32_16x16x32_bf16 v[18:21], v[168:171], v[210:213], v[18:21]
	v_mfma_f32_16x16x32_bf16 v[6:9], v[148:151], v[238:241], v[6:9]
	v_mfma_f32_16x16x32_bf16 v[2:5], v[168:171], v[238:241], v[2:5]
	v_mfma_f32_16x16x32_bf16 v[56:59], v[152:155], v[180:183], v[56:59]
	v_mfma_f32_16x16x32_bf16 v[52:55], v[172:175], v[180:183], v[52:55]
	v_mfma_f32_16x16x32_bf16 v[40:43], v[152:155], v[192:195], v[40:43]
	v_mfma_f32_16x16x32_bf16 v[36:39], v[172:175], v[192:195], v[36:39]
	v_mfma_f32_16x16x32_bf16 v[22:25], v[152:155], v[234:237], v[22:25]
	v_mfma_f32_16x16x32_bf16 v[18:21], v[172:175], v[234:237], v[18:21]
	v_mfma_f32_16x16x32_bf16 v[6:9], v[152:155], v[242:245], v[6:9]
	v_mfma_f32_16x16x32_bf16 v[2:5], v[172:175], v[242:245], v[2:5]
	s_barrier
	s_add_i32 s49, s49, 2
	s_add_u32 s13, s13, 0x10000
	s_addc_u32 s28, s28, 0
	s_cmp_gt_u32 s49, 61
	s_mov_b64 s[60:61], s[62:63]
	s_cbranch_scc0 .LBB0_877
	s_nop 0
	s_nop 0
	s_nop 0
	s_nop 0
	s_nop 0
	s_nop 0
	s_and_b64 vcc, exec, s[46:47]
	s_cbranch_vccz .LBB0_880
	s_barrier

.LBB0_1070:
	s_add_u32 s34, s12, 0xfff00080
	s_addc_u32 s35, s13, -1
	s_nop 0
	s_add_i32 s48, 0, 0x10000
	s_cmp_eq_u32 s59, 28
	s_cselect_b32 s67, s61, s35
	s_cselect_b32 s66, s60, s34
	s_cselect_b32 s65, s63, s58
	s_cselect_b32 s64, s62, s28
	s_nop 0
	s_add_i32 s49, 0, 0x14000
	ds_read_b128 v[100:103], v2 offset:0
	ds_read_b128 v[112:115], v2 offset:1024
	ds_read_b128 v[172:175], v2 offset:2048
	ds_read_b128 v[188:191], v2 offset:3072
	ds_read_b128 v[192:195], v2 offset:16384
	ds_read_b128 v[200:203], v2 offset:17408
	ds_read_b128 v[204:207], v2 offset:18432
	ds_read_b128 v[210:213], v2 offset:19456
	s_add_i32 m0, s29, 0xc000
	ds_read_b128 v[216:219], v197
	ds_read_b128 v[220:223], v197 offset:1024
	ds_read_b128 v[224:227], v197 offset:2048
	ds_read_b128 v[228:231], v197 offset:3072
	ds_read_b128 v[232:235], v197 offset:4096
	ds_read_b128 v[236:239], v197 offset:5120
	ds_read_b128 v[240:243], v197 offset:6144
	ds_read_b128 v[244:247], v197 offset:7168
	global_load_lds_dwordx4 v184, s[12:13]
	s_add_i32 m0, s29, 0xe000
	s_nop 0
	s_nop 0
	global_load_lds_dwordx4 v186, s[12:13]
	s_waitcnt vmcnt(8) lgkmcnt(0)
	s_barrier
	v_mfma_i32_16x16x64_i8 v[168:171], v[100:103], v[216:219], v[168:171]
	v_mfma_i32_16x16x64_i8 v[160:163], v[172:175], v[216:219], v[160:163]
	v_mfma_i32_16x16x64_i8 v[152:155], v[100:103], v[224:227], v[152:155]
	v_mfma_i32_16x16x64_i8 v[144:147], v[172:175], v[224:227], v[144:147]
	v_mfma_i32_16x16x64_i8 v[136:139], v[100:103], v[232:235], v[136:139]
	v_mfma_i32_16x16x64_i8 v[128:131], v[172:175], v[232:235], v[128:131]
	v_mfma_i32_16x16x64_i8 v[120:123], v[100:103], v[240:243], v[120:123]
	v_mfma_i32_16x16x64_i8 v[108:111], v[172:175], v[240:243], v[108:111]
	v_mfma_i32_16x16x64_i8 v[168:171], v[112:115], v[220:223], v[168:171]
	v_mfma_i32_16x16x64_i8 v[160:163], v[188:191], v[220:223], v[160:163]
	v_mfma_i32_16x16x64_i8 v[152:155], v[112:115], v[228:231], v[152:155]
	v_mfma_i32_16x16x64_i8 v[144:147], v[188:191], v[228:231], v[144:147]
	v_mfma_i32_16x16x64_i8 v[136:139], v[112:115], v[236:239], v[136:139]
	v_mfma_i32_16x16x64_i8 v[128:131], v[188:191], v[236:239], v[128:131]
	v_mfma_i32_16x16x64_i8 v[120:123], v[112:115], v[244:247], v[120:123]
	v_mfma_i32_16x16x64_i8 v[108:111], v[188:191], v[244:247], v[108:111]
	v_mfma_i32_16x16x64_i8 v[164:167], v[192:195], v[216:219], v[164:167]
	v_mfma_i32_16x16x64_i8 v[156:159], v[204:207], v[216:219], v[156:159]
	v_mfma_i32_16x16x64_i8 v[148:151], v[192:195], v[224:227], v[148:151]
	v_mfma_i32_16x16x64_i8 v[140:143], v[204:207], v[224:227], v[140:143]
	v_mfma_i32_16x16x64_i8 v[132:135], v[192:195], v[232:235], v[132:135]
	v_mfma_i32_16x16x64_i8 v[124:127], v[204:207], v[232:235], v[124:127]
	v_mfma_i32_16x16x64_i8 v[116:119], v[192:195], v[240:243], v[116:119]
	v_mfma_i32_16x16x64_i8 v[104:107], v[204:207], v[240:243], v[104:107]
	v_mfma_i32_16x16x64_i8 v[164:167], v[200:203], v[220:223], v[164:167]
	v_mfma_i32_16x16x64_i8 v[156:159], v[210:213], v[220:223], v[156:159]
	v_mfma_i32_16x16x64_i8 v[148:151], v[200:203], v[228:231], v[148:151]
	v_mfma_i32_16x16x64_i8 v[140:143], v[210:213], v[228:231], v[140:143]
	v_mfma_i32_16x16x64_i8 v[132:135], v[200:203], v[236:239], v[132:135]
	v_mfma_i32_16x16x64_i8 v[124:127], v[210:213], v[236:239], v[124:127]
	v_mfma_i32_16x16x64_i8 v[116:119], v[200:203], v[244:247], v[116:119]
	v_mfma_i32_16x16x64_i8 v[104:107], v[210:213], v[244:247], v[104:107]
	s_barrier
	s_add_i32 s34, s48, s0
	s_mov_b32 m0, s34
	s_nop 0
	ds_read_b128 v[216:219], v197 offset:16384
	ds_read_b128 v[220:223], v197 offset:17408
	ds_read_b128 v[224:227], v197 offset:18432
	ds_read_b128 v[228:231], v197 offset:19456
	ds_read_b128 v[232:235], v197 offset:20480
	ds_read_b128 v[236:239], v197 offset:21504
	ds_read_b128 v[240:243], v197 offset:22528
	ds_read_b128 v[244:247], v197 offset:23552
	global_load_lds_dwordx4 v176, s[64:65]
	s_add_i32 m0, s34, 0x2000
	s_add_u32 s34, s64, 0x4000
	s_addc_u32 s35, s65, 0
	s_add_i32 s48, s49, s0
	global_load_lds_dwordx4 v180, s[64:65]
	s_mov_b32 m0, s48
	s_nop 0
	global_load_lds_dwordx4 v176, s[34:35]
	s_add_i32 m0, s48, 0x2000
	s_nop 0
	s_nop 0
	global_load_lds_dwordx4 v180, s[34:35]
	s_mov_b32 m0, s29
	s_nop 0
	global_load_lds_dwordx4 v178, s[66:67]
	s_mov_b32 m0, s45
	s_nop 0
	global_load_lds_dwordx4 v182, s[66:67]
	s_waitcnt vmcnt(8) lgkmcnt(0)
	s_barrier
	v_mfma_i32_16x16x64_i8 v[96:99], v[100:103], v[216:219], v[96:99]
	v_mfma_i32_16x16x64_i8 v[88:91], v[172:175], v[216:219], v[88:91]
	v_mfma_i32_16x16x64_i8 v[80:83], v[100:103], v[224:227], v[80:83]
	v_mfma_i32_16x16x64_i8 v[72:75], v[172:175], v[224:227], v[72:75]
	v_mfma_i32_16x16x64_i8 v[64:67], v[100:103], v[232:235], v[64:67]
	v_mfma_i32_16x16x64_i8 v[56:59], v[172:175], v[232:235], v[56:59]
	v_mfma_i32_16x16x64_i8 v[48:51], v[100:103], v[240:243], v[48:51]
	v_mfma_i32_16x16x64_i8 v[40:43], v[172:175], v[240:243], v[40:43]
	v_mfma_i32_16x16x64_i8 v[96:99], v[112:115], v[220:223], v[96:99]
	v_mfma_i32_16x16x64_i8 v[88:91], v[188:191], v[220:223], v[88:91]
	v_mfma_i32_16x16x64_i8 v[80:83], v[112:115], v[228:231], v[80:83]
	v_mfma_i32_16x16x64_i8 v[72:75], v[188:191], v[228:231], v[72:75]
	v_mfma_i32_16x16x64_i8 v[64:67], v[112:115], v[236:239], v[64:67]
	v_mfma_i32_16x16x64_i8 v[56:59], v[188:191], v[236:239], v[56:59]
	v_mfma_i32_16x16x64_i8 v[48:51], v[112:115], v[244:247], v[48:51]
	v_mfma_i32_16x16x64_i8 v[40:43], v[188:191], v[244:247], v[40:43]
	v_mfma_i32_16x16x64_i8 v[92:95], v[192:195], v[216:219], v[92:95]
	v_mfma_i32_16x16x64_i8 v[84:87], v[204:207], v[216:219], v[84:87]
	v_mfma_i32_16x16x64_i8 v[76:79], v[192:195], v[224:227], v[76:79]
	v_mfma_i32_16x16x64_i8 v[68:71], v[204:207], v[224:227], v[68:71]
	v_mfma_i32_16x16x64_i8 v[60:63], v[192:195], v[232:235], v[60:63]
	v_mfma_i32_16x16x64_i8 v[52:55], v[204:207], v[232:235], v[52:55]
	v_mfma_i32_16x16x64_i8 v[44:47], v[192:195], v[240:243], v[44:47]
	v_mfma_i32_16x16x64_i8 v[36:39], v[204:207], v[240:243], v[36:39]
	v_mfma_i32_16x16x64_i8 v[92:95], v[200:203], v[220:223], v[92:95]
	v_mfma_i32_16x16x64_i8 v[84:87], v[210:213], v[220:223], v[84:87]
	v_mfma_i32_16x16x64_i8 v[76:79], v[200:203], v[228:231], v[76:79]
	v_mfma_i32_16x16x64_i8 v[68:71], v[210:213], v[228:231], v[68:71]
	v_mfma_i32_16x16x64_i8 v[60:63], v[200:203], v[236:239], v[60:63]
	v_mfma_i32_16x16x64_i8 v[52:55], v[210:213], v[236:239], v[52:55]
	v_mfma_i32_16x16x64_i8 v[44:47], v[200:203], v[244:247], v[44:47]
	v_mfma_i32_16x16x64_i8 v[36:39], v[210:213], v[244:247], v[36:39]
	s_barrier
	s_nop 0
	s_add_i32 s48, 0, 0x18000
	s_add_i32 s49, 0, 0x1c000
	ds_read_b128 v[100:103], v2 offset:32768
	ds_read_b128 v[112:115], v2 offset:33792
	ds_read_b128 v[172:175], v2 offset:34816
	ds_read_b128 v[188:191], v2 offset:35840
	ds_read_b128 v[192:195], v2 offset:49152
	ds_read_b128 v[200:203], v2 offset:50176
	ds_read_b128 v[204:207], v2 offset:51200
	ds_read_b128 v[210:213], v2 offset:52224
	s_add_u32 s34, s66, 0x100000
	s_addc_u32 s35, s67, 0
	s_mov_b32 m0, s82
	ds_read_b128 v[216:219], v197 offset:32768
	ds_read_b128 v[220:223], v197 offset:33792
	ds_read_b128 v[224:227], v197 offset:34816
	ds_read_b128 v[228:231], v197 offset:35840
	ds_read_b128 v[232:235], v197 offset:36864
	ds_read_b128 v[236:239], v197 offset:37888
	ds_read_b128 v[240:243], v197 offset:38912
	ds_read_b128 v[244:247], v197 offset:39936
	global_load_lds_dwordx4 v178, s[34:35]
	s_mov_b32 m0, s90
	s_nop 0
	global_load_lds_dwordx4 v182, s[34:35]
	s_waitcnt vmcnt(8) lgkmcnt(0)
	s_barrier
	v_mfma_i32_16x16x64_i8 v[168:171], v[100:103], v[216:219], v[168:171]
	v_mfma_i32_16x16x64_i8 v[160:163], v[172:175], v[216:219], v[160:163]
	v_mfma_i32_16x16x64_i8 v[152:155], v[100:103], v[224:227], v[152:155]
	v_mfma_i32_16x16x64_i8 v[144:147], v[172:175], v[224:227], v[144:147]
	v_mfma_i32_16x16x64_i8 v[136:139], v[100:103], v[232:235], v[136:139]
	v_mfma_i32_16x16x64_i8 v[128:131], v[172:175], v[232:235], v[128:131]
	v_mfma_i32_16x16x64_i8 v[120:123], v[100:103], v[240:243], v[120:123]
	v_mfma_i32_16x16x64_i8 v[108:111], v[172:175], v[240:243], v[108:111]
	v_mfma_i32_16x16x64_i8 v[168:171], v[112:115], v[220:223], v[168:171]
	v_mfma_i32_16x16x64_i8 v[160:163], v[188:191], v[220:223], v[160:163]
	v_mfma_i32_16x16x64_i8 v[152:155], v[112:115], v[228:231], v[152:155]
	v_mfma_i32_16x16x64_i8 v[144:147], v[188:191], v[228:231], v[144:147]
	v_mfma_i32_16x16x64_i8 v[136:139], v[112:115], v[236:239], v[136:139]
	v_mfma_i32_16x16x64_i8 v[128:131], v[188:191], v[236:239], v[128:131]
	v_mfma_i32_16x16x64_i8 v[120:123], v[112:115], v[244:247], v[120:123]
	v_mfma_i32_16x16x64_i8 v[108:111], v[188:191], v[244:247], v[108:111]
	v_mfma_i32_16x16x64_i8 v[164:167], v[192:195], v[216:219], v[164:167]
	v_mfma_i32_16x16x64_i8 v[156:159], v[204:207], v[216:219], v[156:159]
	v_mfma_i32_16x16x64_i8 v[148:151], v[192:195], v[224:227], v[148:151]
	v_mfma_i32_16x16x64_i8 v[140:143], v[204:207], v[224:227], v[140:143]
	v_mfma_i32_16x16x64_i8 v[132:135], v[192:195], v[232:235], v[132:135]
	v_mfma_i32_16x16x64_i8 v[124:127], v[204:207], v[232:235], v[124:127]
	v_mfma_i32_16x16x64_i8 v[116:119], v[192:195], v[240:243], v[116:119]
	v_mfma_i32_16x16x64_i8 v[104:107], v[204:207], v[240:243], v[104:107]
	v_mfma_i32_16x16x64_i8 v[164:167], v[200:203], v[220:223], v[164:167]
	v_mfma_i32_16x16x64_i8 v[156:159], v[210:213], v[220:223], v[156:159]
	v_mfma_i32_16x16x64_i8 v[148:151], v[200:203], v[228:231], v[148:151]
	v_mfma_i32_16x16x64_i8 v[140:143], v[210:213], v[228:231], v[140:143]
	v_mfma_i32_16x16x64_i8 v[132:135], v[200:203], v[236:239], v[132:135]
	v_mfma_i32_16x16x64_i8 v[124:127], v[210:213], v[236:239], v[124:127]
	v_mfma_i32_16x16x64_i8 v[116:119], v[200:203], v[244:247], v[116:119]
	v_mfma_i32_16x16x64_i8 v[104:107], v[210:213], v[244:247], v[104:107]
	s_barrier
	s_nop 0
	s_add_u32 s34, s64, 0x8000
	s_addc_u32 s35, s65, 0
	s_add_i32 s48, s48, s0
	s_mov_b32 m0, s48
	s_nop 0
	ds_read_b128 v[216:219], v197 offset:49152
	ds_read_b128 v[220:223], v197 offset:50176
	ds_read_b128 v[224:227], v197 offset:51200
	ds_read_b128 v[228:231], v197 offset:52224
	ds_read_b128 v[232:235], v197 offset:53248
	ds_read_b128 v[236:239], v197 offset:54272
	ds_read_b128 v[240:243], v197 offset:55296
	ds_read_b128 v[244:247], v197 offset:56320
	global_load_lds_dwordx4 v176, s[34:35]
	s_add_i32 m0, s48, 0x2000
	s_mov_b64 s[100:101], s[34:35]
	s_nop 0
	s_add_u32 s34, s64, 0xc000
	s_addc_u32 s35, s65, 0
	s_add_i32 s48, s49, s0
	global_load_lds_dwordx4 v180, s[100:101]
	s_mov_b32 m0, s48
	s_nop 0
	global_load_lds_dwordx4 v176, s[34:35]
	s_add_i32 m0, s48, 0x2000
	s_nop 0
	s_nop 0
	global_load_lds_dwordx4 v180, s[34:35]
	s_mov_b32 m0, s91
	s_nop 0
	s_add_u32 s100, s66, s92
	s_addc_u32 s101, s67, s93
	global_load_lds_dwordx4 v178, s[100:101]
	s_mov_b32 m0, s30
	s_nop 0
	s_add_u32 s100, s66, s92
	s_addc_u32 s101, s67, s93
	global_load_lds_dwordx4 v182, s[100:101]
	s_waitcnt vmcnt(8) lgkmcnt(0)
	s_barrier
	v_mfma_i32_16x16x64_i8 v[96:99], v[100:103], v[216:219], v[96:99]
	v_mfma_i32_16x16x64_i8 v[88:91], v[172:175], v[216:219], v[88:91]
	v_mfma_i32_16x16x64_i8 v[80:83], v[100:103], v[224:227], v[80:83]
	v_mfma_i32_16x16x64_i8 v[72:75], v[172:175], v[224:227], v[72:75]
	v_mfma_i32_16x16x64_i8 v[64:67], v[100:103], v[232:235], v[64:67]
	v_mfma_i32_16x16x64_i8 v[56:59], v[172:175], v[232:235], v[56:59]
	v_mfma_i32_16x16x64_i8 v[48:51], v[100:103], v[240:243], v[48:51]
	v_mfma_i32_16x16x64_i8 v[40:43], v[172:175], v[240:243], v[40:43]
	v_mfma_i32_16x16x64_i8 v[96:99], v[112:115], v[220:223], v[96:99]
	v_mfma_i32_16x16x64_i8 v[88:91], v[188:191], v[220:223], v[88:91]
	v_mfma_i32_16x16x64_i8 v[80:83], v[112:115], v[228:231], v[80:83]
	v_mfma_i32_16x16x64_i8 v[72:75], v[188:191], v[228:231], v[72:75]
	v_mfma_i32_16x16x64_i8 v[64:67], v[112:115], v[236:239], v[64:67]
	v_mfma_i32_16x16x64_i8 v[56:59], v[188:191], v[236:239], v[56:59]
	v_mfma_i32_16x16x64_i8 v[48:51], v[112:115], v[244:247], v[48:51]
	v_mfma_i32_16x16x64_i8 v[40:43], v[188:191], v[244:247], v[40:43]
	v_mfma_i32_16x16x64_i8 v[92:95], v[192:195], v[216:219], v[92:95]
	v_mfma_i32_16x16x64_i8 v[84:87], v[204:207], v[216:219], v[84:87]
	v_mfma_i32_16x16x64_i8 v[76:79], v[192:195], v[224:227], v[76:79]
	v_mfma_i32_16x16x64_i8 v[68:71], v[204:207], v[224:227], v[68:71]
	v_mfma_i32_16x16x64_i8 v[60:63], v[192:195], v[232:235], v[60:63]
	v_mfma_i32_16x16x64_i8 v[52:55], v[204:207], v[232:235], v[52:55]
	v_mfma_i32_16x16x64_i8 v[44:47], v[192:195], v[240:243], v[44:47]
	v_mfma_i32_16x16x64_i8 v[36:39], v[204:207], v[240:243], v[36:39]
	v_mfma_i32_16x16x64_i8 v[92:95], v[200:203], v[220:223], v[92:95]
	v_mfma_i32_16x16x64_i8 v[84:87], v[210:213], v[220:223], v[84:87]
	v_mfma_i32_16x16x64_i8 v[76:79], v[200:203], v[228:231], v[76:79]
	v_mfma_i32_16x16x64_i8 v[68:71], v[210:213], v[228:231], v[68:71]
	v_mfma_i32_16x16x64_i8 v[60:63], v[200:203], v[236:239], v[60:63]
	v_mfma_i32_16x16x64_i8 v[52:55], v[210:213], v[236:239], v[52:55]
	v_mfma_i32_16x16x64_i8 v[44:47], v[200:203], v[244:247], v[44:47]
	v_mfma_i32_16x16x64_i8 v[36:39], v[210:213], v[244:247], v[36:39]
	s_barrier
	s_add_i32 s59, s59, 2
	s_add_u32 s28, s28, 0x10000
	s_addc_u32 s58, s58, 0
	s_nop 0
	s_add_u32 s12, s12, 0x100
	s_addc_u32 s13, s13, 0
	s_cmp_gt_u32 s59, 29
	s_cbranch_scc0 .LBB0_1070
	s_nop 0
	s_nop 0
	s_nop 0
	s_nop 0
	s_nop 0
	s_and_b64 vcc, exec, s[46:47]
	s_cbranch_vccz .LBB0_1073
	s_barrier

.LBB0_1261:
	s_add_u32 s42, s22, 0x100
	s_addc_u32 s43, s23, 0
	s_nop 0
	s_add_i32 s34, 0, 0x10000
	s_cmpk_eq_i32 s60, 0xa8
	s_cselect_b32 s51, s19, s43
	s_cselect_b32 s50, s18, s42
	s_cselect_b32 s49, s21, s59
	s_cselect_b32 s48, s20, s58
	s_nop 0
	s_add_i32 s35, 0, 0x14000
	ds_read_b128 v[132:135], v188 offset:0
	ds_read_b128 v[136:139], v188 offset:1024
	ds_read_b128 v[140:143], v188 offset:2048
	ds_read_b128 v[144:147], v188 offset:3072
	ds_read_b128 v[148:151], v188 offset:16384
	ds_read_b128 v[152:155], v188 offset:17408
	ds_read_b128 v[168:171], v188 offset:18432
	ds_read_b128 v[172:175], v188 offset:19456
	s_add_i32 m0, s29, 0xc000
	ds_read_b128 v[176:179], v187
	ds_read_b128 v[180:183], v187 offset:1024
	ds_read_b128 v[192:195], v187 offset:2048
	ds_read_b128 v[210:213], v187 offset:3072
	ds_read_b128 v[232:235], v187 offset:4096
	ds_read_b128 v[236:239], v187 offset:5120
	ds_read_b128 v[240:243], v187 offset:6144
	ds_read_b128 v[244:247], v187 offset:7168
	global_load_lds_dwordx4 v164, s[22:23]
	s_add_i32 m0, s29, 0xe000
	s_nop 0
	s_nop 0
	global_load_lds_dwordx4 v166, s[22:23]
	s_waitcnt vmcnt(8) lgkmcnt(0)
	s_barrier
	v_mfma_f32_16x16x32_bf16 v[128:131], v[132:135], v[176:179], v[128:131]
	v_mfma_f32_16x16x32_bf16 v[124:127], v[140:143], v[176:179], v[124:127]
	v_mfma_f32_16x16x32_bf16 v[112:115], v[132:135], v[192:195], v[112:115]
	v_mfma_f32_16x16x32_bf16 v[108:111], v[140:143], v[192:195], v[108:111]
	v_mfma_f32_16x16x32_bf16 v[96:99], v[132:135], v[232:235], v[96:99]
	v_mfma_f32_16x16x32_bf16 v[92:95], v[140:143], v[232:235], v[92:95]
	v_mfma_f32_16x16x32_bf16 v[80:83], v[132:135], v[240:243], v[80:83]
	v_mfma_f32_16x16x32_bf16 v[76:79], v[140:143], v[240:243], v[76:79]
	v_mfma_f32_16x16x32_bf16 v[128:131], v[136:139], v[180:183], v[128:131]
	v_mfma_f32_16x16x32_bf16 v[124:127], v[144:147], v[180:183], v[124:127]
	v_mfma_f32_16x16x32_bf16 v[112:115], v[136:139], v[210:213], v[112:115]
	v_mfma_f32_16x16x32_bf16 v[108:111], v[144:147], v[210:213], v[108:111]
	v_mfma_f32_16x16x32_bf16 v[96:99], v[136:139], v[236:239], v[96:99]
	v_mfma_f32_16x16x32_bf16 v[92:95], v[144:147], v[236:239], v[92:95]
	v_mfma_f32_16x16x32_bf16 v[80:83], v[136:139], v[244:247], v[80:83]
	v_mfma_f32_16x16x32_bf16 v[76:79], v[144:147], v[244:247], v[76:79]
	v_mfma_f32_16x16x32_bf16 v[120:123], v[148:151], v[176:179], v[120:123]
	v_mfma_f32_16x16x32_bf16 v[116:119], v[168:171], v[176:179], v[116:119]
	v_mfma_f32_16x16x32_bf16 v[104:107], v[148:151], v[192:195], v[104:107]
	v_mfma_f32_16x16x32_bf16 v[100:103], v[168:171], v[192:195], v[100:103]
	v_mfma_f32_16x16x32_bf16 v[88:91], v[148:151], v[232:235], v[88:91]
	v_mfma_f32_16x16x32_bf16 v[84:87], v[168:171], v[232:235], v[84:87]
	v_mfma_f32_16x16x32_bf16 v[72:75], v[148:151], v[240:243], v[72:75]
	v_mfma_f32_16x16x32_bf16 v[68:71], v[168:171], v[240:243], v[68:71]
	v_mfma_f32_16x16x32_bf16 v[120:123], v[152:155], v[180:183], v[120:123]
	v_mfma_f32_16x16x32_bf16 v[116:119], v[172:175], v[180:183], v[116:119]
	v_mfma_f32_16x16x32_bf16 v[104:107], v[152:155], v[210:213], v[104:107]
	v_mfma_f32_16x16x32_bf16 v[100:103], v[172:175], v[210:213], v[100:103]
	v_mfma_f32_16x16x32_bf16 v[88:91], v[152:155], v[236:239], v[88:91]
	v_mfma_f32_16x16x32_bf16 v[84:87], v[172:175], v[236:239], v[84:87]
	v_mfma_f32_16x16x32_bf16 v[72:75], v[152:155], v[244:247], v[72:75]
	v_mfma_f32_16x16x32_bf16 v[68:71], v[172:175], v[244:247], v[68:71]
	s_barrier
	s_add_i32 s22, s34, s0
	s_mov_b32 m0, s22
	s_nop 0
	ds_read_b128 v[176:179], v187 offset:16384
	ds_read_b128 v[180:183], v187 offset:17408
	ds_read_b128 v[192:195], v187 offset:18432
	ds_read_b128 v[210:213], v187 offset:19456
	ds_read_b128 v[232:235], v187 offset:20480
	ds_read_b128 v[236:239], v187 offset:21504
	ds_read_b128 v[240:243], v187 offset:22528
	ds_read_b128 v[244:247], v187 offset:23552
	global_load_lds_dwordx4 v156, s[48:49]
	s_add_i32 m0, s22, 0x2000
	s_add_u32 s22, s48, 0x4000
	s_addc_u32 s23, s49, 0
	s_add_i32 s34, s35, s0
	global_load_lds_dwordx4 v160, s[48:49]
	s_mov_b32 m0, s34
	s_nop 0
	global_load_lds_dwordx4 v156, s[22:23]
	s_add_i32 m0, s34, 0x2000
	s_nop 0
	s_nop 0
	global_load_lds_dwordx4 v160, s[22:23]
	s_mov_b32 m0, s29
	s_nop 0
	global_load_lds_dwordx4 v158, s[50:51]
	s_mov_b32 m0, s45
	s_nop 0
	global_load_lds_dwordx4 v162, s[50:51]
	s_waitcnt vmcnt(8) lgkmcnt(0)
	s_barrier
	v_mfma_f32_16x16x32_bf16 v[64:67], v[132:135], v[176:179], v[64:67]
	v_mfma_f32_16x16x32_bf16 v[60:63], v[140:143], v[176:179], v[60:63]
	v_mfma_f32_16x16x32_bf16 v[48:51], v[132:135], v[192:195], v[48:51]
	v_mfma_f32_16x16x32_bf16 v[44:47], v[140:143], v[192:195], v[44:47]
	v_mfma_f32_16x16x32_bf16 v[30:33], v[132:135], v[232:235], v[30:33]
	v_mfma_f32_16x16x32_bf16 v[26:29], v[140:143], v[232:235], v[26:29]
	v_mfma_f32_16x16x32_bf16 v[14:17], v[132:135], v[240:243], v[14:17]
	v_mfma_f32_16x16x32_bf16 v[10:13], v[140:143], v[240:243], v[10:13]
	v_mfma_f32_16x16x32_bf16 v[64:67], v[136:139], v[180:183], v[64:67]
	v_mfma_f32_16x16x32_bf16 v[60:63], v[144:147], v[180:183], v[60:63]
	v_mfma_f32_16x16x32_bf16 v[48:51], v[136:139], v[210:213], v[48:51]
	v_mfma_f32_16x16x32_bf16 v[44:47], v[144:147], v[210:213], v[44:47]
	v_mfma_f32_16x16x32_bf16 v[30:33], v[136:139], v[236:239], v[30:33]
	v_mfma_f32_16x16x32_bf16 v[26:29], v[144:147], v[236:239], v[26:29]
	v_mfma_f32_16x16x32_bf16 v[14:17], v[136:139], v[244:247], v[14:17]
	v_mfma_f32_16x16x32_bf16 v[10:13], v[144:147], v[244:247], v[10:13]
	v_mfma_f32_16x16x32_bf16 v[56:59], v[148:151], v[176:179], v[56:59]
	v_mfma_f32_16x16x32_bf16 v[52:55], v[168:171], v[176:179], v[52:55]
	v_mfma_f32_16x16x32_bf16 v[40:43], v[148:151], v[192:195], v[40:43]
	v_mfma_f32_16x16x32_bf16 v[36:39], v[168:171], v[192:195], v[36:39]
	v_mfma_f32_16x16x32_bf16 v[22:25], v[148:151], v[232:235], v[22:25]
	v_mfma_f32_16x16x32_bf16 v[18:21], v[168:171], v[232:235], v[18:21]
	v_mfma_f32_16x16x32_bf16 v[6:9], v[148:151], v[240:243], v[6:9]
	v_mfma_f32_16x16x32_bf16 v[2:5], v[168:171], v[240:243], v[2:5]
	v_mfma_f32_16x16x32_bf16 v[56:59], v[152:155], v[180:183], v[56:59]
	v_mfma_f32_16x16x32_bf16 v[52:55], v[172:175], v[180:183], v[52:55]
	v_mfma_f32_16x16x32_bf16 v[40:43], v[152:155], v[210:213], v[40:43]
	v_mfma_f32_16x16x32_bf16 v[36:39], v[172:175], v[210:213], v[36:39]
	v_mfma_f32_16x16x32_bf16 v[22:25], v[152:155], v[236:239], v[22:25]
	v_mfma_f32_16x16x32_bf16 v[18:21], v[172:175], v[236:239], v[18:21]
	v_mfma_f32_16x16x32_bf16 v[6:9], v[152:155], v[244:247], v[6:9]
	v_mfma_f32_16x16x32_bf16 v[2:5], v[172:175], v[244:247], v[2:5]
	s_barrier
	s_nop 0
	s_add_i32 s34, 0, 0x18000
	s_add_i32 s35, 0, 0x1c000
	ds_read_b128 v[132:135], v188 offset:32768
	ds_read_b128 v[136:139], v188 offset:33792
	ds_read_b128 v[140:143], v188 offset:34816
	ds_read_b128 v[144:147], v188 offset:35840
	ds_read_b128 v[148:151], v188 offset:49152
	ds_read_b128 v[152:155], v188 offset:50176
	ds_read_b128 v[168:171], v188 offset:51200
	ds_read_b128 v[172:175], v188 offset:52224
	s_add_u32 s22, s50, 0x2b0000
	s_addc_u32 s23, s51, 0
	s_mov_b32 m0, s82
	ds_read_b128 v[176:179], v187 offset:32768
	ds_read_b128 v[180:183], v187 offset:33792
	ds_read_b128 v[192:195], v187 offset:34816
	ds_read_b128 v[210:213], v187 offset:35840
	ds_read_b128 v[232:235], v187 offset:36864
	ds_read_b128 v[236:239], v187 offset:37888
	ds_read_b128 v[240:243], v187 offset:38912
	ds_read_b128 v[244:247], v187 offset:39936
	global_load_lds_dwordx4 v158, s[22:23]
	s_mov_b32 m0, s90
	s_nop 0
	global_load_lds_dwordx4 v162, s[22:23]
	s_waitcnt vmcnt(8) lgkmcnt(0)
	s_barrier
	v_mfma_f32_16x16x32_bf16 v[128:131], v[132:135], v[176:179], v[128:131]
	v_mfma_f32_16x16x32_bf16 v[124:127], v[140:143], v[176:179], v[124:127]
	v_mfma_f32_16x16x32_bf16 v[112:115], v[132:135], v[192:195], v[112:115]
	v_mfma_f32_16x16x32_bf16 v[108:111], v[140:143], v[192:195], v[108:111]
	v_mfma_f32_16x16x32_bf16 v[96:99], v[132:135], v[232:235], v[96:99]
	v_mfma_f32_16x16x32_bf16 v[92:95], v[140:143], v[232:235], v[92:95]
	v_mfma_f32_16x16x32_bf16 v[80:83], v[132:135], v[240:243], v[80:83]
	v_mfma_f32_16x16x32_bf16 v[76:79], v[140:143], v[240:243], v[76:79]
	v_mfma_f32_16x16x32_bf16 v[128:131], v[136:139], v[180:183], v[128:131]
	v_mfma_f32_16x16x32_bf16 v[124:127], v[144:147], v[180:183], v[124:127]
	v_mfma_f32_16x16x32_bf16 v[112:115], v[136:139], v[210:213], v[112:115]
	v_mfma_f32_16x16x32_bf16 v[108:111], v[144:147], v[210:213], v[108:111]
	v_mfma_f32_16x16x32_bf16 v[96:99], v[136:139], v[236:239], v[96:99]
	v_mfma_f32_16x16x32_bf16 v[92:95], v[144:147], v[236:239], v[92:95]
	v_mfma_f32_16x16x32_bf16 v[80:83], v[136:139], v[244:247], v[80:83]
	v_mfma_f32_16x16x32_bf16 v[76:79], v[144:147], v[244:247], v[76:79]
	v_mfma_f32_16x16x32_bf16 v[120:123], v[148:151], v[176:179], v[120:123]
	v_mfma_f32_16x16x32_bf16 v[116:119], v[168:171], v[176:179], v[116:119]
	v_mfma_f32_16x16x32_bf16 v[104:107], v[148:151], v[192:195], v[104:107]
	v_mfma_f32_16x16x32_bf16 v[100:103], v[168:171], v[192:195], v[100:103]
	v_mfma_f32_16x16x32_bf16 v[88:91], v[148:151], v[232:235], v[88:91]
	v_mfma_f32_16x16x32_bf16 v[84:87], v[168:171], v[232:235], v[84:87]
	v_mfma_f32_16x16x32_bf16 v[72:75], v[148:151], v[240:243], v[72:75]
	v_mfma_f32_16x16x32_bf16 v[68:71], v[168:171], v[240:243], v[68:71]
	v_mfma_f32_16x16x32_bf16 v[120:123], v[152:155], v[180:183], v[120:123]
	v_mfma_f32_16x16x32_bf16 v[116:119], v[172:175], v[180:183], v[116:119]
	v_mfma_f32_16x16x32_bf16 v[104:107], v[152:155], v[210:213], v[104:107]
	v_mfma_f32_16x16x32_bf16 v[100:103], v[172:175], v[210:213], v[100:103]
	v_mfma_f32_16x16x32_bf16 v[88:91], v[152:155], v[236:239], v[88:91]
	v_mfma_f32_16x16x32_bf16 v[84:87], v[172:175], v[236:239], v[84:87]
	v_mfma_f32_16x16x32_bf16 v[72:75], v[152:155], v[244:247], v[72:75]
	v_mfma_f32_16x16x32_bf16 v[68:71], v[172:175], v[244:247], v[68:71]
	s_barrier
	s_nop 0
	s_add_u32 s22, s48, 0x8000
	s_addc_u32 s23, s49, 0
	s_add_i32 s34, s34, s0
	s_mov_b32 m0, s34
	s_nop 0
	ds_read_b128 v[176:179], v187 offset:49152
	ds_read_b128 v[180:183], v187 offset:50176
	ds_read_b128 v[192:195], v187 offset:51200
	ds_read_b128 v[210:213], v187 offset:52224
	ds_read_b128 v[232:235], v187 offset:53248
	ds_read_b128 v[236:239], v187 offset:54272
	ds_read_b128 v[240:243], v187 offset:55296
	ds_read_b128 v[244:247], v187 offset:56320
	global_load_lds_dwordx4 v156, s[22:23]
	s_add_i32 m0, s34, 0x2000
	s_mov_b64 s[100:101], s[22:23]
	s_nop 0
	s_add_u32 s22, s48, 0xc000
	s_addc_u32 s23, s49, 0
	s_add_i32 s34, s35, s0
	global_load_lds_dwordx4 v160, s[100:101]
	s_mov_b32 m0, s34
	s_nop 0
	global_load_lds_dwordx4 v156, s[22:23]
	s_add_i32 m0, s34, 0x2000
	s_nop 0
	s_nop 0
	global_load_lds_dwordx4 v160, s[22:23]
	s_mov_b32 m0, s91
	s_nop 0
	s_add_u32 s100, s50, s92
	s_addc_u32 s101, s51, s93
	global_load_lds_dwordx4 v158, s[100:101]
	s_mov_b32 m0, s30
	s_nop 0
	s_add_u32 s100, s50, s92
	s_addc_u32 s101, s51, s93
	global_load_lds_dwordx4 v162, s[100:101]
	s_waitcnt vmcnt(8) lgkmcnt(0)
	s_barrier
	v_mfma_f32_16x16x32_bf16 v[64:67], v[132:135], v[176:179], v[64:67]
	v_mfma_f32_16x16x32_bf16 v[60:63], v[140:143], v[176:179], v[60:63]
	v_mfma_f32_16x16x32_bf16 v[48:51], v[132:135], v[192:195], v[48:51]
	v_mfma_f32_16x16x32_bf16 v[44:47], v[140:143], v[192:195], v[44:47]
	v_mfma_f32_16x16x32_bf16 v[30:33], v[132:135], v[232:235], v[30:33]
	v_mfma_f32_16x16x32_bf16 v[26:29], v[140:143], v[232:235], v[26:29]
	v_mfma_f32_16x16x32_bf16 v[14:17], v[132:135], v[240:243], v[14:17]
	v_mfma_f32_16x16x32_bf16 v[10:13], v[140:143], v[240:243], v[10:13]
	v_mfma_f32_16x16x32_bf16 v[64:67], v[136:139], v[180:183], v[64:67]
	v_mfma_f32_16x16x32_bf16 v[60:63], v[144:147], v[180:183], v[60:63]
	v_mfma_f32_16x16x32_bf16 v[48:51], v[136:139], v[210:213], v[48:51]
	v_mfma_f32_16x16x32_bf16 v[44:47], v[144:147], v[210:213], v[44:47]
	v_mfma_f32_16x16x32_bf16 v[30:33], v[136:139], v[236:239], v[30:33]
	v_mfma_f32_16x16x32_bf16 v[26:29], v[144:147], v[236:239], v[26:29]
	v_mfma_f32_16x16x32_bf16 v[14:17], v[136:139], v[244:247], v[14:17]
	v_mfma_f32_16x16x32_bf16 v[10:13], v[144:147], v[244:247], v[10:13]
	v_mfma_f32_16x16x32_bf16 v[56:59], v[148:151], v[176:179], v[56:59]
	v_mfma_f32_16x16x32_bf16 v[52:55], v[168:171], v[176:179], v[52:55]
	v_mfma_f32_16x16x32_bf16 v[40:43], v[148:151], v[192:195], v[40:43]
	v_mfma_f32_16x16x32_bf16 v[36:39], v[168:171], v[192:195], v[36:39]
	v_mfma_f32_16x16x32_bf16 v[22:25], v[148:151], v[232:235], v[22:25]
	v_mfma_f32_16x16x32_bf16 v[18:21], v[168:171], v[232:235], v[18:21]
	v_mfma_f32_16x16x32_bf16 v[6:9], v[148:151], v[240:243], v[6:9]
	v_mfma_f32_16x16x32_bf16 v[2:5], v[168:171], v[240:243], v[2:5]
	v_mfma_f32_16x16x32_bf16 v[56:59], v[152:155], v[180:183], v[56:59]
	v_mfma_f32_16x16x32_bf16 v[52:55], v[172:175], v[180:183], v[52:55]
	v_mfma_f32_16x16x32_bf16 v[40:43], v[152:155], v[210:213], v[40:43]
	v_mfma_f32_16x16x32_bf16 v[36:39], v[172:175], v[210:213], v[36:39]
	v_mfma_f32_16x16x32_bf16 v[22:25], v[152:155], v[236:239], v[22:25]
	v_mfma_f32_16x16x32_bf16 v[18:21], v[172:175], v[236:239], v[18:21]
	v_mfma_f32_16x16x32_bf16 v[6:9], v[152:155], v[244:247], v[6:9]
	v_mfma_f32_16x16x32_bf16 v[2:5], v[172:175], v[244:247], v[2:5]
	s_barrier
	s_add_i32 s60, s60, 2
	s_add_u32 s58, s58, 0x10000
	s_addc_u32 s59, s59, 0
	s_cmpk_gt_u32 s60, 0xa9
	s_mov_b64 s[22:23], s[42:43]
	s_cbranch_scc0 .LBB0_1261
	s_nop 0
	s_nop 0
	s_nop 0
	s_nop 0
	s_nop 0
	s_nop 0
	s_and_b64 vcc, exec, s[46:47]
	s_cbranch_vccz .LBB0_1264
	s_barrier
